# scan loop v7: the 32 H-row ds_write_b32 paired into 16 ds_write2_b32 (8 per-lane row-group bases set once per task)
# baseline (speedup 1.0000x reference)
.LBB0_563:
	s_and_b32 s13, s6, 0xff
	s_lshl_b32 s0, s13, 2
	v_mov_b32_e32 v0, s0
	global_load_dword v2, v0, s[38:39]
	s_lshl_b32 s4, s13, 6
	v_or_b32_e32 v0, s4, v174
	v_lshlrev_b32_e32 v3, 2, v0
	global_load_dword v21, v3, s[58:59]
	global_load_dword v20, v3, s[36:37]
	s_and_b32 s2, s10, 0x1800
	v_or_b32_e32 v1, s2, v182
	v_lshlrev_b32_e32 v1, 3, v1
	s_bfe_u32 s0, s12, 0x70001
	v_and_b32_e32 v1, 0xc180, v1
	v_or_b32_e32 v1, s0, v1
	v_lshlrev_b32_e32 v132, 10, v1
	v_lshl_add_u64 v[150:151], v[144:145], 0, v[132:133]
	v_lshl_add_u64 v[152:153], v[146:147], 0, v[132:133]
	v_lshl_add_u64 v[154:155], v[148:149], 0, v[132:133]
	v_lshlrev_b32_e32 v132, 6, v0
	v_lshl_add_u64 v[0:1], v[136:137], 0, v[132:133]
	global_load_dwordx4 v[4:7], v[0:1], off
	global_load_dwordx4 v[8:11], v[0:1], off offset:16
	v_lshl_add_u64 v[0:1], v[134:135], 0, v[132:133]
	global_load_dwordx4 v[12:15], v[0:1], off
	global_load_dwordx4 v[16:19], v[0:1], off offset:16
	v_or_b32_e32 v0, s4, v173
	v_lshlrev_b32_e32 v22, 2, v0
	v_or_b32_e32 v132, 0x800, v132
	s_bfe_u32 s16, s6, 0x70001
	v_mov_b32_e32 v188, 0
	v_mov_b32_e32 v189, v133
	s_waitcnt vmcnt(6)
	v_mul_f32_e32 v0, 0x3fb8aa3b, v2
	v_exp_f32_e32 v0, v0
	global_load_dword v2, v22, s[58:59]
	global_load_dword v1, v22, s[36:37]
	s_waitcnt vmcnt(7)
	v_mov_b32_e32 v22, v21
	v_mov_b32_e32 v25, v21
	v_mul_f32_e32 v23, v0, v21
	s_waitcnt vmcnt(6)
	v_mul_f32_e32 v24, v0, v20
	v_mul_f32_e32 v23, 0x3fb8aa3b, v23
	v_mul_f32_e32 v24, 0.15915494, v24
	v_exp_f32_e32 v23, v23
	v_sin_f32_e32 v26, v24
	v_cos_f32_e32 v24, v24
	v_mov_b32_e32 v27, v20
	v_mul_f32_e32 v28, v23, v26
	v_fma_f32 v29, v23, v24, -1.0
	v_mov_b32_e32 v24, v28
	v_mov_b32_e32 v26, v29
	v_pk_mul_f32 v[30:31], v[20:21], v[28:29]
	v_pk_mul_f32 v[22:23], v[22:23], v[24:25] op_sel_hi:[0,1]
	v_pk_mul_f32 v[20:21], v[20:21], v[26:27] op_sel_hi:[0,1]
	v_add_f32_e32 v28, v30, v31
	v_add_f32_e32 v21, v23, v21
	v_sub_f32_e32 v22, v22, v20
	v_div_scale_f32 v20, s[0:1], v21, v21, v28
	v_div_scale_f32 v24, s[0:1], v21, v21, v22
	v_rcp_f32_e32 v25, v20
	v_rcp_f32_e32 v26, v24
	v_div_scale_f32 v23, vcc, v28, v21, v28
	v_fma_f32 v29, -v20, v25, 1.0
	v_fma_f32 v30, -v24, v26, 1.0
	v_fmac_f32_e32 v25, v29, v25
	v_div_scale_f32 v27, s[0:1], v22, v21, v22
	v_fmac_f32_e32 v26, v30, v26
	v_mul_f32_e32 v29, v23, v25
	v_mul_f32_e32 v30, v27, v26
	v_fma_f32 v31, -v20, v29, v23
	v_fma_f32 v32, -v24, v30, v27
	v_fmac_f32_e32 v29, v31, v25
	v_fmac_f32_e32 v30, v32, v26
	v_fma_f32 v20, -v20, v29, v23
	v_fma_f32 v23, -v24, v30, v27
	v_div_fmas_f32 v20, v20, v25, v29
	s_mov_b64 vcc, s[0:1]
	v_div_fmas_f32 v23, v23, v26, v30
	v_div_fixup_f32 v22, v23, v21, v22
	v_div_fixup_f32 v20, v20, v21, v28
	s_waitcnt vmcnt(5)
	v_pk_mul_f32 v[24:25], v[4:5], v[22:23] op_sel_hi:[1,0]
	v_pk_mul_f32 v[26:27], v[6:7], v[22:23] op_sel_hi:[1,0]
	s_waitcnt vmcnt(4)
	v_pk_mul_f32 v[28:29], v[8:9], v[22:23] op_sel_hi:[1,0]
	v_pk_mul_f32 v[30:31], v[10:11], v[22:23] op_sel_hi:[1,0]
	s_waitcnt vmcnt(3)
	v_pk_mul_f32 v[32:33], v[12:13], v[22:23] op_sel_hi:[1,0]
	v_pk_mul_f32 v[34:35], v[14:15], v[22:23] op_sel_hi:[1,0]
	s_waitcnt vmcnt(2)
	v_pk_mul_f32 v[36:37], v[16:17], v[22:23] op_sel_hi:[1,0]
	v_pk_mul_f32 v[22:23], v[18:19], v[22:23] op_sel_hi:[1,0]
	v_pk_fma_f32 v[14:15], v[14:15], v[20:21], v[26:27] op_sel_hi:[1,0,1] neg_lo:[0,0,1] neg_hi:[0,0,1]
	v_pk_fma_f32 v[12:13], v[12:13], v[20:21], v[24:25] op_sel_hi:[1,0,1] neg_lo:[0,0,1] neg_hi:[0,0,1]
	v_pk_fma_f32 v[18:19], v[18:19], v[20:21], v[30:31] op_sel_hi:[1,0,1] neg_lo:[0,0,1] neg_hi:[0,0,1]
	v_pk_fma_f32 v[16:17], v[16:17], v[20:21], v[28:29] op_sel_hi:[1,0,1] neg_lo:[0,0,1] neg_hi:[0,0,1]
	v_pk_fma_f32 v[6:7], v[6:7], v[20:21], v[34:35] op_sel_hi:[1,0,1]
	v_pk_fma_f32 v[4:5], v[4:5], v[20:21], v[32:33] op_sel_hi:[1,0,1]
	v_pk_fma_f32 v[10:11], v[10:11], v[20:21], v[22:23] op_sel_hi:[1,0,1]
	v_pk_fma_f32 v[8:9], v[8:9], v[20:21], v[36:37] op_sel_hi:[1,0,1]
	v_cvt_pk_bf16_f32 v104, v12, v13
	v_cvt_pk_bf16_f32 v105, v14, v15
	v_cvt_pk_bf16_f32 v106, v16, v17
	v_cvt_pk_bf16_f32 v107, v18, v19
	v_cvt_pk_bf16_f32 v92, v4, v5
	v_cvt_pk_bf16_f32 v93, v6, v7
	s_nop 0
	v_cvt_pk_bf16_f32 v94, v8, v9
	v_cvt_pk_bf16_f32 v95, v10, v11
	v_lshl_or_b32 v58, s13, 12, v183
	v_mov_b32_e32 v59, 0
	v_lshl_add_u64 v[60:61], v[138:139], 0, v[58:59]
	v_lshl_add_u64 v[62:63], v[140:141], 0, v[58:59]
	global_load_dwordx4 v[196:199], v[60:61], off
	global_load_dwordx4 v[200:203], v[62:63], off
	global_load_dwordx4 v[204:207], v[60:61], off offset:32
	global_load_dwordx4 v[208:211], v[62:63], off offset:32
	global_load_dwordx4 v[212:215], v[60:61], off offset:64
	global_load_dwordx4 v[216:219], v[62:63], off offset:64
	global_load_dwordx4 v[220:223], v[60:61], off offset:96
	global_load_dwordx4 v[224:227], v[62:63], off offset:96
	global_load_dwordx4 v[228:231], v[60:61], off offset:128
	global_load_dwordx4 v[232:235], v[62:63], off offset:128
	global_load_dwordx4 v[236:239], v[60:61], off offset:160
	global_load_dwordx4 v[240:243], v[62:63], off offset:160
	global_load_dwordx4 v[244:247], v[60:61], off offset:192
	global_load_dwordx4 v[40:43], v[62:63], off offset:192
	global_load_dwordx4 v[44:47], v[60:61], off offset:224
	global_load_dwordx4 v[48:51], v[62:63], off offset:224
	global_load_dword v21, v3, s[58:59] offset:128
	global_load_dword v20, v3, s[36:37] offset:128
	v_lshl_add_u64 v[12:13], v[136:137], 0, v[132:133]
	v_lshl_add_u64 v[22:23], v[134:135], 0, v[132:133]
	global_load_dwordx4 v[4:7], v[12:13], off
	global_load_dwordx4 v[8:11], v[12:13], off offset:16
	s_nop 0
	global_load_dwordx4 v[12:15], v[22:23], off
	global_load_dwordx4 v[16:19], v[22:23], off offset:16
	v_lshl_or_b32 v132, s13, 12, v183
	v_lshl_add_u64 v[22:23], v[138:139], 0, v[132:133]
	s_waitcnt vmcnt(7)
	v_mul_f32_e32 v2, v2, v0
	v_mul_f32_e32 v2, 0x3fb8aa3b, v2
	v_exp_f32_e32 v2, v2
	s_waitcnt vmcnt(5)
	v_mul_f32_e32 v3, v0, v21
	s_waitcnt vmcnt(4)
	v_mul_f32_e32 v25, v0, v20
	v_mul_f32_e32 v3, 0x3fb8aa3b, v3
	v_mul_f32_e32 v25, 0.15915494, v25
	v_exp_f32_e32 v3, v3
	v_sin_f32_e32 v26, v25
	v_cos_f32_e32 v25, v25
	v_mov_b32_e32 v24, v21
	v_mov_b32_e32 v27, v21
	v_mul_f32_e32 v30, v3, v26
	v_fma_f32 v31, v3, v25, -1.0
	v_mov_b32_e32 v29, v20
	v_mov_b32_e32 v26, v30
	v_mov_b32_e32 v28, v31
	v_pk_mul_f32 v[32:33], v[20:21], v[30:31]
	v_pk_mul_f32 v[24:25], v[24:25], v[26:27] op_sel_hi:[0,1]
	v_pk_mul_f32 v[20:21], v[20:21], v[28:29] op_sel_hi:[0,1]
	v_add_f32_e32 v3, v32, v33
	v_add_f32_e32 v21, v25, v21
	v_sub_f32_e32 v24, v24, v20
	v_div_scale_f32 v20, s[0:1], v21, v21, v3
	v_div_scale_f32 v26, s[0:1], v21, v21, v24
	v_rcp_f32_e32 v27, v20
	v_rcp_f32_e32 v28, v26
	v_div_scale_f32 v25, vcc, v3, v21, v3
	v_fma_f32 v30, -v20, v27, 1.0
	v_fma_f32 v31, -v26, v28, 1.0
	v_fmac_f32_e32 v27, v30, v27
	v_div_scale_f32 v29, s[0:1], v24, v21, v24
	v_fmac_f32_e32 v28, v31, v28
	v_mul_f32_e32 v30, v25, v27
	v_mul_f32_e32 v31, v29, v28
	v_fma_f32 v32, -v20, v30, v25
	v_fma_f32 v33, -v26, v31, v29
	v_fmac_f32_e32 v30, v32, v27
	v_fmac_f32_e32 v31, v33, v28
	v_fma_f32 v20, -v20, v30, v25
	v_fma_f32 v25, -v26, v31, v29
	v_div_fmas_f32 v20, v20, v27, v30
	s_mov_b64 vcc, s[0:1]
	v_div_fixup_f32 v20, v20, v21, v3
	v_div_fmas_f32 v3, v25, v28, v31
	v_div_fixup_f32 v24, v3, v21, v24
	s_waitcnt vmcnt(3)
	v_pk_mul_f32 v[26:27], v[4:5], v[24:25] op_sel_hi:[1,0]
	v_pk_mul_f32 v[28:29], v[6:7], v[24:25] op_sel_hi:[1,0]
	s_waitcnt vmcnt(2)
	v_pk_mul_f32 v[30:31], v[8:9], v[24:25] op_sel_hi:[1,0]
	v_pk_mul_f32 v[32:33], v[10:11], v[24:25] op_sel_hi:[1,0]
	s_waitcnt vmcnt(1)
	v_pk_mul_f32 v[34:35], v[12:13], v[24:25] op_sel_hi:[1,0]
	v_pk_mul_f32 v[36:37], v[14:15], v[24:25] op_sel_hi:[1,0]
	s_waitcnt vmcnt(0)
	v_pk_mul_f32 v[38:39], v[16:17], v[24:25] op_sel_hi:[1,0]
	v_pk_mul_f32 v[24:25], v[18:19], v[24:25] op_sel_hi:[1,0]
	v_pk_fma_f32 v[12:13], v[12:13], v[20:21], v[26:27] op_sel_hi:[1,0,1] neg_lo:[0,0,1] neg_hi:[0,0,1]
	v_pk_fma_f32 v[6:7], v[6:7], v[20:21], v[36:37] op_sel_hi:[1,0,1]
	v_pk_fma_f32 v[4:5], v[4:5], v[20:21], v[34:35] op_sel_hi:[1,0,1]
	v_pk_fma_f32 v[10:11], v[10:11], v[20:21], v[24:25] op_sel_hi:[1,0,1]
	v_pk_fma_f32 v[8:9], v[8:9], v[20:21], v[38:39] op_sel_hi:[1,0,1]
	v_cvt_pk_bf16_f32 v116, v12, v13
	v_lshl_add_u64 v[12:13], v[140:141], 0, v[132:133]
	v_pk_fma_f32 v[14:15], v[14:15], v[20:21], v[28:29] op_sel_hi:[1,0,1] neg_lo:[0,0,1] neg_hi:[0,0,1]
	v_pk_fma_f32 v[18:19], v[18:19], v[20:21], v[32:33] op_sel_hi:[1,0,1] neg_lo:[0,0,1] neg_hi:[0,0,1]
	v_pk_fma_f32 v[16:17], v[16:17], v[20:21], v[30:31] op_sel_hi:[1,0,1] neg_lo:[0,0,1] neg_hi:[0,0,1]
	v_cvt_pk_bf16_f32 v117, v14, v15
	s_lshl_b32 s1, s6, 3
	v_cvt_pk_bf16_f32 v118, v16, v17
	v_cvt_pk_bf16_f32 v119, v18, v19
	v_cvt_pk_bf16_f32 v112, v4, v5
	v_cvt_pk_bf16_f32 v113, v6, v7
	v_cvt_pk_bf16_f32 v114, v8, v9
	v_cvt_pk_bf16_f32 v115, v10, v11
	s_and_b32 s15, s1, 0x1800
	v_or_b32_e32 v3, s15, v174
	v_lshlrev_b32_e32 v3, 3, v3
	s_lshl_b32 s0, s6, 4
	v_and_b32_e32 v3, 0xc080, v3
	s_and_b32 s14, s0, 16
	v_or_b32_e32 v3, s16, v3
	v_or_b32_e32 v132, s14, v176
	v_lshl_or_b32 v3, v3, 9, v177
	v_or3_b32 v14, s14, v175, v3
	v_or_b32_e32 v3, v3, v132
	v_lshlrev_b32_e32 v3, 1, v3
	v_lshlrev_b32_e32 v14, 1, v14
	v_or_b32_e32 v15, 16, v3
	v_mul_f32_e32 v0, v0, v1
	v_mul_f32_e32 v1, 0.15915494, v0
	v_cos_f32_e32 v0, v1
	v_sin_f32_e32 v1, v1
	s_mov_b64 s[0:1], 0
	s_mov_b32 s16, 0
	v_pk_mul_f32 v[198:199], v[126:127], v[198:199]
	v_pk_mul_f32 v[196:197], v[124:125], v[196:197]
	v_pk_mul_f32 v[202:203], v[130:131], v[202:203]
	v_pk_mul_f32 v[200:201], v[128:129], v[200:201]
	s_nop 0
	v_cvt_pk_bf16_f32 v64, v196, v200
	v_cvt_pk_bf16_f32 v65, v197, v201
	v_cvt_pk_bf16_f32 v66, v198, v202
	v_cvt_pk_bf16_f32 v67, v199, v203
	v_pk_mul_f32 v[206:207], v[126:127], v[206:207]
	v_pk_mul_f32 v[204:205], v[124:125], v[204:205]
	v_pk_mul_f32 v[210:211], v[130:131], v[210:211]
	v_pk_mul_f32 v[208:209], v[128:129], v[208:209]
	s_nop 0
	v_cvt_pk_bf16_f32 v68, v204, v208
	v_cvt_pk_bf16_f32 v69, v205, v209
	v_cvt_pk_bf16_f32 v70, v206, v210
	v_cvt_pk_bf16_f32 v71, v207, v211
	v_pk_mul_f32 v[214:215], v[126:127], v[214:215]
	v_pk_mul_f32 v[212:213], v[124:125], v[212:213]
	v_pk_mul_f32 v[218:219], v[130:131], v[218:219]
	v_pk_mul_f32 v[216:217], v[128:129], v[216:217]
	s_nop 0
	v_cvt_pk_bf16_f32 v72, v212, v216
	v_cvt_pk_bf16_f32 v73, v213, v217
	v_cvt_pk_bf16_f32 v74, v214, v218
	v_cvt_pk_bf16_f32 v75, v215, v219
	v_pk_mul_f32 v[222:223], v[126:127], v[222:223]
	v_pk_mul_f32 v[220:221], v[124:125], v[220:221]
	v_pk_mul_f32 v[226:227], v[130:131], v[226:227]
	v_pk_mul_f32 v[224:225], v[128:129], v[224:225]
	s_nop 0
	v_cvt_pk_bf16_f32 v76, v220, v224
	v_cvt_pk_bf16_f32 v77, v221, v225
	v_cvt_pk_bf16_f32 v78, v222, v226
	v_cvt_pk_bf16_f32 v79, v223, v227
	v_pk_mul_f32 v[230:231], v[126:127], v[230:231]
	v_pk_mul_f32 v[228:229], v[124:125], v[228:229]
	v_pk_mul_f32 v[234:235], v[130:131], v[234:235]
	v_pk_mul_f32 v[232:233], v[128:129], v[232:233]
	s_nop 0
	v_cvt_pk_bf16_f32 v84, v228, v232
	v_cvt_pk_bf16_f32 v85, v229, v233
	v_cvt_pk_bf16_f32 v86, v230, v234
	v_cvt_pk_bf16_f32 v87, v231, v235
	v_pk_mul_f32 v[238:239], v[126:127], v[238:239]
	v_pk_mul_f32 v[236:237], v[124:125], v[236:237]
	v_pk_mul_f32 v[242:243], v[130:131], v[242:243]
	v_pk_mul_f32 v[240:241], v[128:129], v[240:241]
	s_nop 0
	v_cvt_pk_bf16_f32 v88, v236, v240
	v_cvt_pk_bf16_f32 v89, v237, v241
	v_cvt_pk_bf16_f32 v90, v238, v242
	v_cvt_pk_bf16_f32 v91, v239, v243
	v_pk_mul_f32 v[246:247], v[126:127], v[246:247]
	v_pk_mul_f32 v[244:245], v[124:125], v[244:245]
	v_pk_mul_f32 v[42:43], v[130:131], v[42:43]
	v_pk_mul_f32 v[40:41], v[128:129], v[40:41]
	s_nop 0
	v_cvt_pk_bf16_f32 v96, v244, v40
	v_cvt_pk_bf16_f32 v97, v245, v41
	v_cvt_pk_bf16_f32 v98, v246, v42
	v_cvt_pk_bf16_f32 v99, v247, v43
	v_lshl_add_u64 v[12:13], v[142:143], 0, s[4:5]
	s_bfe_u32 s4, s6, 0x10001
	v_pk_mul_f32 v[46:47], v[126:127], v[46:47]
	v_pk_mul_f32 v[44:45], v[124:125], v[44:45]
	v_pk_mul_f32 v[50:51], v[130:131], v[50:51]
	v_pk_mul_f32 v[48:49], v[128:129], v[48:49]
	s_nop 0
	v_cvt_pk_bf16_f32 v108, v44, v48
	v_cvt_pk_bf16_f32 v109, v45, v49
	v_cvt_pk_bf16_f32 v110, v46, v50
	v_cvt_pk_bf16_f32 v111, v47, v51
	global_load_dwordx4 v[100:103], v[12:13], off
	global_load_dwordx4 v[80:83], v[12:13], off offset:32
	global_load_dwordx4 v[120:123], v14, s[54:55]
	global_load_dwordx2 v[158:159], v3, s[54:55]
	global_load_dwordx2 v[156:157], v15, s[54:55]
	v_or_b32_e32 v3, s2, v174
	v_pk_mul_f32 v[160:161], v[0:1], v[2:3] op_sel_hi:[1,0]
	v_lshrrev_b32_e32 v187, 3, v3
	v_pk_mov_b32 v[162:163], v[160:161], v[160:161] op_sel:[1,0]
	v_mov_b32_e32 v164, v160
	v_mov_b32_e32 v165, v160
	v_mov_b32_e32 v166, v161
	v_mov_b32_e32 v167, v161
	v_mov_b32_e32 v184, 0xbdd2d3e8
	global_load_dwordx4 v[168:171], v[152:153], off
	s_add_u32 s0, s0, 0x40000
	s_addc_u32 s1, s1, 0
	v_lshl_add_u64 v[216:217], v[152:153], 0, s[0:1]
	global_load_dwordx4 v[156:159], v[216:217], off
	s_add_u32 s0, s0, 0x40000
	s_addc_u32 s1, s1, 0
	v_lshl_add_u64 v[216:217], v[152:153], 0, s[0:1]
	global_load_dwordx4 v[178:181], v[216:217], off
	s_and_b32 s18, s16, 0x2000
	s_and_b32 s17, s2, 0x1f00
	s_or_b32 s17, s17, s13
	s_lshl_b32 s17, s17, 12
	s_and_b32 s17, s17, 0x1ffc000
	v_add_u32_e32 v222, s2, v174
	v_and_or_b32 v223, v187, 14, s4
	v_lshlrev_b32_e32 v225, 5, v222
	v_lshlrev_b32_e32 v226, 1, v222
	v_lshl_or_b32 v227, v223, 9, s18
	v_and_b32_e32 v222, 0x1e0, v225
	v_and_b32_e32 v223, 16, v226
	v_or_b32_e32 v224, v222, v132
	v_bitop3_b32 v222, v222, v223, v132 bitop3:0x36
	v_or_b32_e32 v225, s17, v227
	v_bitop3_b32 v226, v224, v223, 8 bitop3:0x36
	v_or_b32_e32 v227, v222, v225
	v_or_b32_e32 v254, v226, v225
	v_lshlrev_b32_e32 v253, 1, v227
	v_lshlrev_b32_e32 v254, 1, v254
	s_mov_b64 s[14:15], s[90:91]
	v_add_u32_e32 v222, 18432, v185
	v_add_u32_e32 v223, 19520, v185
	v_add_u32_e32 v224, 20608, v185
	v_add_u32_e32 v225, 21696, v185
	v_add_u32_e32 v226, 22784, v185
	v_add_u32_e32 v227, 23872, v185
	v_add_u32_e32 v190, 24960, v185
	v_add_u32_e32 v191, 26048, v185
	s_branch .Lscan_tile

.Lscan_go_0:
	v_mfma_f32_32x32x16_bf16 v[0:15], v[120:123], v[104:107], 0
	s_addk_i32 s16, 0x800
	v_mfma_f32_32x32x16_bf16 v[16:31], v[120:123], v[116:119], 0
	v_mfma_f32_32x32x16_bf16 v[32:47], v[120:123], v[92:95], 0
	v_mfma_f32_32x32x16_bf16 v[196:211], v[120:123], v[112:115], 0
	v_mov_b32_e32 v218, v120
	v_mov_b32_e32 v219, v121
	v_mov_b32_e32 v220, v122
	v_mov_b32_e32 v221, v123
	s_nop 0
	v_permlane32_swap_b32_e32 v218, v220
	v_permlane32_swap_b32_e32 v219, v221
	s_add_u32 s0, s0, 0x40000
	s_addc_u32 s1, s1, 0
	v_lshl_add_u64 v[216:217], v[152:153], 0, s[0:1]
	global_load_dwordx4 v[120:123], v[216:217], off
	v_lshlrev_b32_e32 v228, 16, v218
	v_and_b32_e32 v229, 0xffff0000, v218
	v_lshlrev_b32_e32 v230, 16, v219
	v_and_b32_e32 v231, 0xffff0000, v219
	v_lshlrev_b32_e32 v232, 16, v220
	v_and_b32_e32 v233, 0xffff0000, v220
	v_lshlrev_b32_e32 v251, 16, v221
	v_and_b32_e32 v252, 0xffff0000, v221
	v_permlane32_swap_b32_e32 v0, v16
	v_permlane32_swap_b32_e32 v1, v17
	v_permlane32_swap_b32_e32 v2, v18
	v_permlane32_swap_b32_e32 v3, v19
	v_permlane32_swap_b32_e32 v4, v20
	v_permlane32_swap_b32_e32 v5, v21
	v_permlane32_swap_b32_e32 v6, v22
	v_permlane32_swap_b32_e32 v7, v23
	v_permlane32_swap_b32_e32 v8, v24
	v_permlane32_swap_b32_e32 v9, v25
	v_permlane32_swap_b32_e32 v10, v26
	v_permlane32_swap_b32_e32 v11, v27
	v_permlane32_swap_b32_e32 v12, v28
	v_permlane32_swap_b32_e32 v13, v29
	v_permlane32_swap_b32_e32 v14, v30
	v_permlane32_swap_b32_e32 v15, v31
	v_permlane32_swap_b32_e32 v32, v196
	v_permlane32_swap_b32_e32 v33, v197
	v_permlane32_swap_b32_e32 v34, v198
	v_permlane32_swap_b32_e32 v35, v199
	v_permlane32_swap_b32_e32 v36, v200
	v_permlane32_swap_b32_e32 v37, v201
	v_permlane32_swap_b32_e32 v38, v202
	v_permlane32_swap_b32_e32 v39, v203
	v_permlane32_swap_b32_e32 v40, v204
	v_permlane32_swap_b32_e32 v41, v205
	v_permlane32_swap_b32_e32 v42, v206
	v_permlane32_swap_b32_e32 v43, v207
	v_permlane32_swap_b32_e32 v44, v208
	v_permlane32_swap_b32_e32 v45, v209
	v_permlane32_swap_b32_e32 v46, v210
	v_permlane32_swap_b32_e32 v47, v211
	v_fmac_f32_e32 v0, v160, v188
	v_fmac_f32_e32 v32, v160, v189
	v_fma_f32 v0, -v161, v189, v0
	v_fmac_f32_e32 v32, v161, v188
	v_fmac_f32_e32 v1, v160, v0
	v_fmac_f32_e32 v33, v160, v32
	v_cvt_pk_bf16_f32 v212, v0, v32
	v_fma_f32 v1, -v161, v32, v1
	v_fmac_f32_e32 v33, v161, v0
	v_fmac_f32_e32 v2, v160, v1
	v_fmac_f32_e32 v34, v160, v33
	v_cvt_pk_bf16_f32 v213, v1, v33
	v_fma_f32 v2, -v161, v33, v2
	v_fmac_f32_e32 v34, v161, v1
	ds_write2_b32 v222, v212, v213 offset0:0 offset1:68
	v_fmac_f32_e32 v3, v160, v2
	v_fmac_f32_e32 v35, v160, v34
	v_cvt_pk_bf16_f32 v214, v2, v34
	v_fma_f32 v3, -v161, v34, v3
	v_fmac_f32_e32 v35, v161, v2
	v_fmac_f32_e32 v16, v160, v3
	v_fmac_f32_e32 v196, v160, v35
	v_cvt_pk_bf16_f32 v215, v3, v35
	v_fma_f32 v16, -v161, v35, v16
	v_fmac_f32_e32 v196, v161, v3
	ds_write2_b32 v222, v214, v215 offset0:136 offset1:204
	v_fmac_f32_e32 v17, v160, v16
	v_fmac_f32_e32 v197, v160, v196
	v_cvt_pk_bf16_f32 v212, v16, v196
	v_fma_f32 v17, -v161, v196, v17
	v_fmac_f32_e32 v197, v161, v16
	v_fmac_f32_e32 v18, v160, v17
	v_fmac_f32_e32 v198, v160, v197
	v_cvt_pk_bf16_f32 v213, v17, v197
	v_fma_f32 v18, -v161, v197, v18
	v_fmac_f32_e32 v198, v161, v17
	ds_write2_b32 v223, v212, v213 offset0:0 offset1:68
	v_fmac_f32_e32 v19, v160, v18
	v_fmac_f32_e32 v199, v160, v198
	v_cvt_pk_bf16_f32 v214, v18, v198
	v_fma_f32 v19, -v161, v198, v19
	v_fmac_f32_e32 v199, v161, v18
	v_fmac_f32_e32 v4, v160, v19
	v_fmac_f32_e32 v36, v160, v199
	v_cvt_pk_bf16_f32 v215, v19, v199
	v_fma_f32 v4, -v161, v199, v4
	v_fmac_f32_e32 v36, v161, v19
	ds_write2_b32 v223, v214, v215 offset0:136 offset1:204
	v_fmac_f32_e32 v5, v160, v4
	v_fmac_f32_e32 v37, v160, v36
	v_cvt_pk_bf16_f32 v212, v4, v36
	v_fma_f32 v5, -v161, v36, v5
	v_fmac_f32_e32 v37, v161, v4
	v_fmac_f32_e32 v6, v160, v5
	v_fmac_f32_e32 v38, v160, v37
	v_cvt_pk_bf16_f32 v213, v5, v37
	v_fma_f32 v6, -v161, v37, v6
	v_fmac_f32_e32 v38, v161, v5
	ds_write2_b32 v224, v212, v213 offset0:0 offset1:68
	v_fmac_f32_e32 v7, v160, v6
	v_fmac_f32_e32 v39, v160, v38
	v_cvt_pk_bf16_f32 v214, v6, v38
	v_fma_f32 v7, -v161, v38, v7
	v_fmac_f32_e32 v39, v161, v6
	v_fmac_f32_e32 v20, v160, v7
	v_fmac_f32_e32 v200, v160, v39
	v_cvt_pk_bf16_f32 v215, v7, v39
	v_fma_f32 v20, -v161, v39, v20
	v_fmac_f32_e32 v200, v161, v7
	ds_write2_b32 v224, v214, v215 offset0:136 offset1:204
	v_fmac_f32_e32 v21, v160, v20
	v_fmac_f32_e32 v201, v160, v200
	v_cvt_pk_bf16_f32 v212, v20, v200
	v_fma_f32 v21, -v161, v200, v21
	v_fmac_f32_e32 v201, v161, v20
	v_fmac_f32_e32 v22, v160, v21
	v_fmac_f32_e32 v202, v160, v201
	v_cvt_pk_bf16_f32 v213, v21, v201
	v_fma_f32 v22, -v161, v201, v22
	v_fmac_f32_e32 v202, v161, v21
	ds_write2_b32 v225, v212, v213 offset0:0 offset1:68
	v_fmac_f32_e32 v23, v160, v22
	v_fmac_f32_e32 v203, v160, v202
	v_cvt_pk_bf16_f32 v214, v22, v202
	v_fma_f32 v23, -v161, v202, v23
	v_fmac_f32_e32 v203, v161, v22
	v_fmac_f32_e32 v8, v160, v23
	v_fmac_f32_e32 v40, v160, v203
	v_cvt_pk_bf16_f32 v215, v23, v203
	v_fma_f32 v8, -v161, v203, v8
	v_fmac_f32_e32 v40, v161, v23
	ds_write2_b32 v225, v214, v215 offset0:136 offset1:204
	v_fmac_f32_e32 v9, v160, v8
	v_fmac_f32_e32 v41, v160, v40
	v_cvt_pk_bf16_f32 v212, v8, v40
	v_fma_f32 v9, -v161, v40, v9
	v_fmac_f32_e32 v41, v161, v8
	v_fmac_f32_e32 v10, v160, v9
	v_fmac_f32_e32 v42, v160, v41
	v_cvt_pk_bf16_f32 v213, v9, v41
	v_fma_f32 v10, -v161, v41, v10
	v_fmac_f32_e32 v42, v161, v9
	ds_write2_b32 v226, v212, v213 offset0:0 offset1:68
	v_fmac_f32_e32 v11, v160, v10
	v_fmac_f32_e32 v43, v160, v42
	v_cvt_pk_bf16_f32 v214, v10, v42
	v_fma_f32 v11, -v161, v42, v11
	v_fmac_f32_e32 v43, v161, v10
	v_fmac_f32_e32 v24, v160, v11
	v_fmac_f32_e32 v204, v160, v43
	v_cvt_pk_bf16_f32 v215, v11, v43
	v_fma_f32 v24, -v161, v43, v24
	v_fmac_f32_e32 v204, v161, v11
	ds_write2_b32 v226, v214, v215 offset0:136 offset1:204
	v_fmac_f32_e32 v25, v160, v24
	v_fmac_f32_e32 v205, v160, v204
	v_cvt_pk_bf16_f32 v212, v24, v204
	v_fma_f32 v25, -v161, v204, v25
	v_fmac_f32_e32 v205, v161, v24
	v_fmac_f32_e32 v26, v160, v25
	v_fmac_f32_e32 v206, v160, v205
	v_cvt_pk_bf16_f32 v213, v25, v205
	v_fma_f32 v26, -v161, v205, v26
	v_fmac_f32_e32 v206, v161, v25
	ds_write2_b32 v227, v212, v213 offset0:0 offset1:68
	v_fmac_f32_e32 v27, v160, v26
	v_fmac_f32_e32 v207, v160, v206
	v_cvt_pk_bf16_f32 v214, v26, v206
	v_fma_f32 v27, -v161, v206, v27
	v_fmac_f32_e32 v207, v161, v26
	v_fmac_f32_e32 v12, v160, v27
	v_fmac_f32_e32 v44, v160, v207
	v_cvt_pk_bf16_f32 v215, v27, v207
	v_fma_f32 v12, -v161, v207, v12
	v_fmac_f32_e32 v44, v161, v27
	ds_write2_b32 v227, v214, v215 offset0:136 offset1:204
	v_fmac_f32_e32 v13, v160, v12
	v_fmac_f32_e32 v45, v160, v44
	v_cvt_pk_bf16_f32 v212, v12, v44
	v_fma_f32 v13, -v161, v44, v13
	v_fmac_f32_e32 v45, v161, v12
	v_fmac_f32_e32 v14, v160, v13
	v_fmac_f32_e32 v46, v160, v45
	v_cvt_pk_bf16_f32 v213, v13, v45
	v_fma_f32 v14, -v161, v45, v14
	v_fmac_f32_e32 v46, v161, v13
	ds_write2_b32 v190, v212, v213 offset0:0 offset1:68
	v_fmac_f32_e32 v15, v160, v14
	v_fmac_f32_e32 v47, v160, v46
	v_cvt_pk_bf16_f32 v214, v14, v46
	v_fma_f32 v15, -v161, v46, v15
	v_fmac_f32_e32 v47, v161, v14
	v_fmac_f32_e32 v28, v160, v15
	v_fmac_f32_e32 v208, v160, v47
	v_cvt_pk_bf16_f32 v215, v15, v47
	v_fma_f32 v28, -v161, v47, v28
	v_fmac_f32_e32 v208, v161, v15
	ds_write2_b32 v190, v214, v215 offset0:136 offset1:204
	v_fmac_f32_e32 v29, v160, v28
	v_fmac_f32_e32 v209, v160, v208
	v_cvt_pk_bf16_f32 v212, v28, v208
	v_fma_f32 v29, -v161, v208, v29
	v_fmac_f32_e32 v209, v161, v28
	v_fmac_f32_e32 v30, v160, v29
	v_fmac_f32_e32 v210, v160, v209
	v_cvt_pk_bf16_f32 v213, v29, v209
	v_fma_f32 v30, -v161, v209, v30
	v_fmac_f32_e32 v210, v161, v29
	ds_write2_b32 v191, v212, v213 offset0:0 offset1:68
	v_fmac_f32_e32 v31, v160, v30
	v_fmac_f32_e32 v211, v160, v210
	v_cvt_pk_bf16_f32 v214, v30, v210
	v_fma_f32 v31, -v161, v210, v31
	v_fmac_f32_e32 v211, v161, v30
	v_mov_b32_e32 v188, v31
	v_mov_b32_e32 v189, v211
	v_cvt_pk_bf16_f32 v215, v31, v211
	ds_write2_b32 v191, v214, v215 offset0:136 offset1:204
	s_waitcnt lgkmcnt(0)
	ds_read_b128 v[32:35], v186 offset:18432
	ds_read_b128 v[36:39], v186 offset:18464
	ds_read_b128 v[40:43], v186 offset:18496
	ds_read_b128 v[44:47], v186 offset:18528
	ds_read_b128 v[196:199], v186 offset:18560
	ds_read_b128 v[200:203], v186 offset:18592
	ds_read_b128 v[204:207], v186 offset:18624
	ds_read_b128 v[208:211], v186 offset:18656
	s_waitcnt lgkmcnt(7)
	v_mfma_f32_32x32x16_bf16 v[48:63], v[64:67], v[32:35], 0
	v_fmac_f32_e32 v234, v100, v162
	v_fmac_f32_e32 v235, v101, v163
	v_fmac_f32_e32 v236, v102, v164
	v_fmac_f32_e32 v237, v103, v165
	v_fmac_f32_e32 v238, v80, v166
	v_fmac_f32_e32 v239, v81, v167
	v_fmac_f32_e32 v240, v82, v192
	v_fmac_f32_e32 v241, v83, v193
	v_mul_f32_e32 v242, v234, v234
	s_waitcnt lgkmcnt(6)
	v_mfma_f32_32x32x16_bf16 v[48:63], v[68:71], v[36:39], v[48:63]
	v_mul_f32_e32 v243, v235, v235
	v_mul_f32_e32 v244, v236, v236
	v_mul_f32_e32 v245, v237, v237
	v_mul_f32_e32 v246, v238, v238
	v_mul_f32_e32 v247, v239, v239
	v_mul_f32_e32 v248, v240, v240
	v_mul_f32_e32 v249, v241, v241
	v_fmaak_f32 v242, v242, v184, 0xc0135761
	v_fmaak_f32 v243, v243, v184, 0xc0135761
	s_waitcnt lgkmcnt(5)
	v_mfma_f32_32x32x16_bf16 v[48:63], v[72:75], v[40:43], v[48:63]
	v_fmaak_f32 v244, v244, v184, 0xc0135761
	v_fmaak_f32 v245, v245, v184, 0xc0135761
	v_fmaak_f32 v246, v246, v184, 0xc0135761
	v_fmaak_f32 v247, v247, v184, 0xc0135761
	v_fmaak_f32 v248, v248, v184, 0xc0135761
	v_fmaak_f32 v249, v249, v184, 0xc0135761
	v_mul_f32_e32 v242, v234, v242
	v_mul_f32_e32 v243, v235, v243
	v_mul_f32_e32 v244, v236, v244
	s_waitcnt lgkmcnt(4)
	v_mfma_f32_32x32x16_bf16 v[48:63], v[76:79], v[44:47], v[48:63]
	v_mul_f32_e32 v245, v237, v245
	v_mul_f32_e32 v246, v238, v246
	v_mul_f32_e32 v247, v239, v247
	v_mul_f32_e32 v248, v240, v248
	v_mul_f32_e32 v249, v241, v249
	v_exp_f32_e32 v242, v242
	v_exp_f32_e32 v243, v243
	v_exp_f32_e32 v244, v244
	v_exp_f32_e32 v245, v245
	s_waitcnt lgkmcnt(3)
	v_mfma_f32_32x32x16_bf16 v[48:63], v[84:87], v[196:199], v[48:63]
	v_exp_f32_e32 v246, v246
	v_exp_f32_e32 v247, v247
	v_exp_f32_e32 v248, v248
	v_exp_f32_e32 v249, v249
	v_add_f32_e32 v242, 1.0, v242
	v_add_f32_e32 v243, 1.0, v243
	v_add_f32_e32 v244, 1.0, v244
	v_add_f32_e32 v245, 1.0, v245
	s_waitcnt lgkmcnt(2)
	v_mfma_f32_32x32x16_bf16 v[48:63], v[88:91], v[200:203], v[48:63]
	v_add_f32_e32 v246, 1.0, v246
	v_add_f32_e32 v247, 1.0, v247
	v_add_f32_e32 v248, 1.0, v248
	v_add_f32_e32 v249, 1.0, v249
	v_rcp_f32_e32 v242, v242
	v_rcp_f32_e32 v243, v243
	v_rcp_f32_e32 v244, v244
	v_rcp_f32_e32 v245, v245
	s_waitcnt lgkmcnt(1)
	v_mfma_f32_32x32x16_bf16 v[48:63], v[96:99], v[204:207], v[48:63]
	v_rcp_f32_e32 v246, v246
	v_rcp_f32_e32 v247, v247
	v_rcp_f32_e32 v248, v248
	v_rcp_f32_e32 v249, v249
	v_mul_f32_e32 v234, v234, v242
	v_mul_f32_e32 v235, v235, v243
	v_mul_f32_e32 v236, v236, v244
	v_mul_f32_e32 v237, v237, v245
	s_waitcnt lgkmcnt(0)
	v_mfma_f32_32x32x16_bf16 v[48:63], v[108:111], v[208:211], v[48:63]
	v_mul_f32_e32 v238, v238, v246
	v_mul_f32_e32 v239, v239, v247
	v_mul_f32_e32 v240, v240, v248
	v_mul_f32_e32 v241, v241, v249
	v_cvt_pk_bf16_f32 v242, v234, v235
	v_cvt_pk_bf16_f32 v243, v236, v237
	v_cvt_pk_bf16_f32 v244, v238, v239
	v_cvt_pk_bf16_f32 v245, v240, v241
	s_cmp_eq_u32 s16, 0x800
	s_cbranch_scc1 .Lscan_nostore
	global_store_dwordx2 v253, v[242:243], s[14:15]
	global_store_dwordx2 v254, v[244:245], s[14:15]
	s_movk_i32 s18, 0x1000
	s_and_b32 s17, s16, 0x3800
	s_cmp_eq_u32 s17, 0x800
	s_cselect_b32 s18, 0x1f9000, s18
	s_add_u32 s14, s14, s18
	s_addc_u32 s15, s15, 0

.Lscan_go_1:
	v_mfma_f32_32x32x16_bf16 v[0:15], v[168:171], v[104:107], 0
	s_addk_i32 s16, 0x800
	v_mfma_f32_32x32x16_bf16 v[16:31], v[168:171], v[116:119], 0
	v_mfma_f32_32x32x16_bf16 v[32:47], v[168:171], v[92:95], 0
	v_mfma_f32_32x32x16_bf16 v[196:211], v[168:171], v[112:115], 0
	v_mov_b32_e32 v218, v168
	v_mov_b32_e32 v219, v169
	v_mov_b32_e32 v220, v170
	v_mov_b32_e32 v221, v171
	s_nop 0
	v_permlane32_swap_b32_e32 v218, v220
	v_permlane32_swap_b32_e32 v219, v221
	s_add_u32 s0, s0, 0x40000
	s_addc_u32 s1, s1, 0
	v_lshl_add_u64 v[216:217], v[152:153], 0, s[0:1]
	global_load_dwordx4 v[168:171], v[216:217], off
	v_lshlrev_b32_e32 v162, 16, v218
	v_and_b32_e32 v163, 0xffff0000, v218
	v_lshlrev_b32_e32 v164, 16, v219
	v_and_b32_e32 v165, 0xffff0000, v219
	v_lshlrev_b32_e32 v166, 16, v220
	v_and_b32_e32 v167, 0xffff0000, v220
	v_lshlrev_b32_e32 v192, 16, v221
	v_and_b32_e32 v193, 0xffff0000, v221
	v_permlane32_swap_b32_e32 v0, v16
	v_permlane32_swap_b32_e32 v1, v17
	v_permlane32_swap_b32_e32 v2, v18
	v_permlane32_swap_b32_e32 v3, v19
	v_permlane32_swap_b32_e32 v4, v20
	v_permlane32_swap_b32_e32 v5, v21
	v_permlane32_swap_b32_e32 v6, v22
	v_permlane32_swap_b32_e32 v7, v23
	v_permlane32_swap_b32_e32 v8, v24
	v_permlane32_swap_b32_e32 v9, v25
	v_permlane32_swap_b32_e32 v10, v26
	v_permlane32_swap_b32_e32 v11, v27
	v_permlane32_swap_b32_e32 v12, v28
	v_permlane32_swap_b32_e32 v13, v29
	v_permlane32_swap_b32_e32 v14, v30
	v_permlane32_swap_b32_e32 v15, v31
	v_permlane32_swap_b32_e32 v32, v196
	v_permlane32_swap_b32_e32 v33, v197
	v_permlane32_swap_b32_e32 v34, v198
	v_permlane32_swap_b32_e32 v35, v199
	v_permlane32_swap_b32_e32 v36, v200
	v_permlane32_swap_b32_e32 v37, v201
	v_permlane32_swap_b32_e32 v38, v202
	v_permlane32_swap_b32_e32 v39, v203
	v_permlane32_swap_b32_e32 v40, v204
	v_permlane32_swap_b32_e32 v41, v205
	v_permlane32_swap_b32_e32 v42, v206
	v_permlane32_swap_b32_e32 v43, v207
	v_permlane32_swap_b32_e32 v44, v208
	v_permlane32_swap_b32_e32 v45, v209
	v_permlane32_swap_b32_e32 v46, v210
	v_permlane32_swap_b32_e32 v47, v211
	v_fmac_f32_e32 v0, v160, v188
	v_fmac_f32_e32 v32, v160, v189
	v_fma_f32 v0, -v161, v189, v0
	v_fmac_f32_e32 v32, v161, v188
	v_fmac_f32_e32 v1, v160, v0
	v_fmac_f32_e32 v33, v160, v32
	v_cvt_pk_bf16_f32 v212, v0, v32
	v_fma_f32 v1, -v161, v32, v1
	v_fmac_f32_e32 v33, v161, v0
	v_fmac_f32_e32 v2, v160, v1
	v_fmac_f32_e32 v34, v160, v33
	v_cvt_pk_bf16_f32 v213, v1, v33
	v_fma_f32 v2, -v161, v33, v2
	v_fmac_f32_e32 v34, v161, v1
	ds_write2_b32 v222, v212, v213 offset0:0 offset1:68
	v_fmac_f32_e32 v3, v160, v2
	v_fmac_f32_e32 v35, v160, v34
	v_cvt_pk_bf16_f32 v214, v2, v34
	v_fma_f32 v3, -v161, v34, v3
	v_fmac_f32_e32 v35, v161, v2
	v_fmac_f32_e32 v16, v160, v3
	v_fmac_f32_e32 v196, v160, v35
	v_cvt_pk_bf16_f32 v215, v3, v35
	v_fma_f32 v16, -v161, v35, v16
	v_fmac_f32_e32 v196, v161, v3
	ds_write2_b32 v222, v214, v215 offset0:136 offset1:204
	v_fmac_f32_e32 v17, v160, v16
	v_fmac_f32_e32 v197, v160, v196
	v_cvt_pk_bf16_f32 v212, v16, v196
	v_fma_f32 v17, -v161, v196, v17
	v_fmac_f32_e32 v197, v161, v16
	v_fmac_f32_e32 v18, v160, v17
	v_fmac_f32_e32 v198, v160, v197
	v_cvt_pk_bf16_f32 v213, v17, v197
	v_fma_f32 v18, -v161, v197, v18
	v_fmac_f32_e32 v198, v161, v17
	ds_write2_b32 v223, v212, v213 offset0:0 offset1:68
	v_fmac_f32_e32 v19, v160, v18
	v_fmac_f32_e32 v199, v160, v198
	v_cvt_pk_bf16_f32 v214, v18, v198
	v_fma_f32 v19, -v161, v198, v19
	v_fmac_f32_e32 v199, v161, v18
	v_fmac_f32_e32 v4, v160, v19
	v_fmac_f32_e32 v36, v160, v199
	v_cvt_pk_bf16_f32 v215, v19, v199
	v_fma_f32 v4, -v161, v199, v4
	v_fmac_f32_e32 v36, v161, v19
	ds_write2_b32 v223, v214, v215 offset0:136 offset1:204
	v_fmac_f32_e32 v5, v160, v4
	v_fmac_f32_e32 v37, v160, v36
	v_cvt_pk_bf16_f32 v212, v4, v36
	v_fma_f32 v5, -v161, v36, v5
	v_fmac_f32_e32 v37, v161, v4
	v_fmac_f32_e32 v6, v160, v5
	v_fmac_f32_e32 v38, v160, v37
	v_cvt_pk_bf16_f32 v213, v5, v37
	v_fma_f32 v6, -v161, v37, v6
	v_fmac_f32_e32 v38, v161, v5
	ds_write2_b32 v224, v212, v213 offset0:0 offset1:68
	v_fmac_f32_e32 v7, v160, v6
	v_fmac_f32_e32 v39, v160, v38
	v_cvt_pk_bf16_f32 v214, v6, v38
	v_fma_f32 v7, -v161, v38, v7
	v_fmac_f32_e32 v39, v161, v6
	v_fmac_f32_e32 v20, v160, v7
	v_fmac_f32_e32 v200, v160, v39
	v_cvt_pk_bf16_f32 v215, v7, v39
	v_fma_f32 v20, -v161, v39, v20
	v_fmac_f32_e32 v200, v161, v7
	ds_write2_b32 v224, v214, v215 offset0:136 offset1:204
	v_fmac_f32_e32 v21, v160, v20
	v_fmac_f32_e32 v201, v160, v200
	v_cvt_pk_bf16_f32 v212, v20, v200
	v_fma_f32 v21, -v161, v200, v21
	v_fmac_f32_e32 v201, v161, v20
	v_fmac_f32_e32 v22, v160, v21
	v_fmac_f32_e32 v202, v160, v201
	v_cvt_pk_bf16_f32 v213, v21, v201
	v_fma_f32 v22, -v161, v201, v22
	v_fmac_f32_e32 v202, v161, v21
	ds_write2_b32 v225, v212, v213 offset0:0 offset1:68
	v_fmac_f32_e32 v23, v160, v22
	v_fmac_f32_e32 v203, v160, v202
	v_cvt_pk_bf16_f32 v214, v22, v202
	v_fma_f32 v23, -v161, v202, v23
	v_fmac_f32_e32 v203, v161, v22
	v_fmac_f32_e32 v8, v160, v23
	v_fmac_f32_e32 v40, v160, v203
	v_cvt_pk_bf16_f32 v215, v23, v203
	v_fma_f32 v8, -v161, v203, v8
	v_fmac_f32_e32 v40, v161, v23
	ds_write2_b32 v225, v214, v215 offset0:136 offset1:204
	v_fmac_f32_e32 v9, v160, v8
	v_fmac_f32_e32 v41, v160, v40
	v_cvt_pk_bf16_f32 v212, v8, v40
	v_fma_f32 v9, -v161, v40, v9
	v_fmac_f32_e32 v41, v161, v8
	v_fmac_f32_e32 v10, v160, v9
	v_fmac_f32_e32 v42, v160, v41
	v_cvt_pk_bf16_f32 v213, v9, v41
	v_fma_f32 v10, -v161, v41, v10
	v_fmac_f32_e32 v42, v161, v9
	ds_write2_b32 v226, v212, v213 offset0:0 offset1:68
	v_fmac_f32_e32 v11, v160, v10
	v_fmac_f32_e32 v43, v160, v42
	v_cvt_pk_bf16_f32 v214, v10, v42
	v_fma_f32 v11, -v161, v42, v11
	v_fmac_f32_e32 v43, v161, v10
	v_fmac_f32_e32 v24, v160, v11
	v_fmac_f32_e32 v204, v160, v43
	v_cvt_pk_bf16_f32 v215, v11, v43
	v_fma_f32 v24, -v161, v43, v24
	v_fmac_f32_e32 v204, v161, v11
	ds_write2_b32 v226, v214, v215 offset0:136 offset1:204
	v_fmac_f32_e32 v25, v160, v24
	v_fmac_f32_e32 v205, v160, v204
	v_cvt_pk_bf16_f32 v212, v24, v204
	v_fma_f32 v25, -v161, v204, v25
	v_fmac_f32_e32 v205, v161, v24
	v_fmac_f32_e32 v26, v160, v25
	v_fmac_f32_e32 v206, v160, v205
	v_cvt_pk_bf16_f32 v213, v25, v205
	v_fma_f32 v26, -v161, v205, v26
	v_fmac_f32_e32 v206, v161, v25
	ds_write2_b32 v227, v212, v213 offset0:0 offset1:68
	v_fmac_f32_e32 v27, v160, v26
	v_fmac_f32_e32 v207, v160, v206
	v_cvt_pk_bf16_f32 v214, v26, v206
	v_fma_f32 v27, -v161, v206, v27
	v_fmac_f32_e32 v207, v161, v26
	v_fmac_f32_e32 v12, v160, v27
	v_fmac_f32_e32 v44, v160, v207
	v_cvt_pk_bf16_f32 v215, v27, v207
	v_fma_f32 v12, -v161, v207, v12
	v_fmac_f32_e32 v44, v161, v27
	ds_write2_b32 v227, v214, v215 offset0:136 offset1:204
	v_fmac_f32_e32 v13, v160, v12
	v_fmac_f32_e32 v45, v160, v44
	v_cvt_pk_bf16_f32 v212, v12, v44
	v_fma_f32 v13, -v161, v44, v13
	v_fmac_f32_e32 v45, v161, v12
	v_fmac_f32_e32 v14, v160, v13
	v_fmac_f32_e32 v46, v160, v45
	v_cvt_pk_bf16_f32 v213, v13, v45
	v_fma_f32 v14, -v161, v45, v14
	v_fmac_f32_e32 v46, v161, v13
	ds_write2_b32 v190, v212, v213 offset0:0 offset1:68
	v_fmac_f32_e32 v15, v160, v14
	v_fmac_f32_e32 v47, v160, v46
	v_cvt_pk_bf16_f32 v214, v14, v46
	v_fma_f32 v15, -v161, v46, v15
	v_fmac_f32_e32 v47, v161, v14
	v_fmac_f32_e32 v28, v160, v15
	v_fmac_f32_e32 v208, v160, v47
	v_cvt_pk_bf16_f32 v215, v15, v47
	v_fma_f32 v28, -v161, v47, v28
	v_fmac_f32_e32 v208, v161, v15
	ds_write2_b32 v190, v214, v215 offset0:136 offset1:204
	v_fmac_f32_e32 v29, v160, v28
	v_fmac_f32_e32 v209, v160, v208
	v_cvt_pk_bf16_f32 v212, v28, v208
	v_fma_f32 v29, -v161, v208, v29
	v_fmac_f32_e32 v209, v161, v28
	v_fmac_f32_e32 v30, v160, v29
	v_fmac_f32_e32 v210, v160, v209
	v_cvt_pk_bf16_f32 v213, v29, v209
	v_fma_f32 v30, -v161, v209, v30
	v_fmac_f32_e32 v210, v161, v29
	ds_write2_b32 v191, v212, v213 offset0:0 offset1:68
	v_fmac_f32_e32 v31, v160, v30
	v_fmac_f32_e32 v211, v160, v210
	v_cvt_pk_bf16_f32 v214, v30, v210
	v_fma_f32 v31, -v161, v210, v31
	v_fmac_f32_e32 v211, v161, v30
	v_mov_b32_e32 v188, v31
	v_mov_b32_e32 v189, v211
	v_cvt_pk_bf16_f32 v215, v31, v211
	ds_write2_b32 v191, v214, v215 offset0:136 offset1:204
	s_waitcnt lgkmcnt(0)
	ds_read_b128 v[32:35], v186 offset:18432
	ds_read_b128 v[36:39], v186 offset:18464
	ds_read_b128 v[40:43], v186 offset:18496
	ds_read_b128 v[44:47], v186 offset:18528
	ds_read_b128 v[196:199], v186 offset:18560
	ds_read_b128 v[200:203], v186 offset:18592
	ds_read_b128 v[204:207], v186 offset:18624
	ds_read_b128 v[208:211], v186 offset:18656
	s_waitcnt lgkmcnt(7)
	v_mfma_f32_32x32x16_bf16 v[234:249], v[64:67], v[32:35], 0
	v_fmac_f32_e32 v48, v100, v228
	v_fmac_f32_e32 v49, v101, v229
	v_fmac_f32_e32 v50, v102, v230
	v_fmac_f32_e32 v51, v103, v231
	v_fmac_f32_e32 v52, v80, v232
	v_fmac_f32_e32 v53, v81, v233
	v_fmac_f32_e32 v54, v82, v251
	v_fmac_f32_e32 v55, v83, v252
	v_mul_f32_e32 v56, v48, v48
	s_waitcnt lgkmcnt(6)
	v_mfma_f32_32x32x16_bf16 v[234:249], v[68:71], v[36:39], v[234:249]
	v_mul_f32_e32 v57, v49, v49
	v_mul_f32_e32 v58, v50, v50
	v_mul_f32_e32 v59, v51, v51
	v_mul_f32_e32 v60, v52, v52
	v_mul_f32_e32 v61, v53, v53
	v_mul_f32_e32 v62, v54, v54
	v_mul_f32_e32 v63, v55, v55
	v_fmaak_f32 v56, v56, v184, 0xc0135761
	v_fmaak_f32 v57, v57, v184, 0xc0135761
	s_waitcnt lgkmcnt(5)
	v_mfma_f32_32x32x16_bf16 v[234:249], v[72:75], v[40:43], v[234:249]
	v_fmaak_f32 v58, v58, v184, 0xc0135761
	v_fmaak_f32 v59, v59, v184, 0xc0135761
	v_fmaak_f32 v60, v60, v184, 0xc0135761
	v_fmaak_f32 v61, v61, v184, 0xc0135761
	v_fmaak_f32 v62, v62, v184, 0xc0135761
	v_fmaak_f32 v63, v63, v184, 0xc0135761
	v_mul_f32_e32 v56, v48, v56
	v_mul_f32_e32 v57, v49, v57
	v_mul_f32_e32 v58, v50, v58
	s_waitcnt lgkmcnt(4)
	v_mfma_f32_32x32x16_bf16 v[234:249], v[76:79], v[44:47], v[234:249]
	v_mul_f32_e32 v59, v51, v59
	v_mul_f32_e32 v60, v52, v60
	v_mul_f32_e32 v61, v53, v61
	v_mul_f32_e32 v62, v54, v62
	v_mul_f32_e32 v63, v55, v63
	v_exp_f32_e32 v56, v56
	v_exp_f32_e32 v57, v57
	v_exp_f32_e32 v58, v58
	v_exp_f32_e32 v59, v59
	s_waitcnt lgkmcnt(3)
	v_mfma_f32_32x32x16_bf16 v[234:249], v[84:87], v[196:199], v[234:249]
	v_exp_f32_e32 v60, v60
	v_exp_f32_e32 v61, v61
	v_exp_f32_e32 v62, v62
	v_exp_f32_e32 v63, v63
	v_add_f32_e32 v56, 1.0, v56
	v_add_f32_e32 v57, 1.0, v57
	v_add_f32_e32 v58, 1.0, v58
	v_add_f32_e32 v59, 1.0, v59
	s_waitcnt lgkmcnt(2)
	v_mfma_f32_32x32x16_bf16 v[234:249], v[88:91], v[200:203], v[234:249]
	v_add_f32_e32 v60, 1.0, v60
	v_add_f32_e32 v61, 1.0, v61
	v_add_f32_e32 v62, 1.0, v62
	v_add_f32_e32 v63, 1.0, v63
	v_rcp_f32_e32 v56, v56
	v_rcp_f32_e32 v57, v57
	v_rcp_f32_e32 v58, v58
	v_rcp_f32_e32 v59, v59
	s_waitcnt lgkmcnt(1)
	v_mfma_f32_32x32x16_bf16 v[234:249], v[96:99], v[204:207], v[234:249]
	v_rcp_f32_e32 v60, v60
	v_rcp_f32_e32 v61, v61
	v_rcp_f32_e32 v62, v62
	v_rcp_f32_e32 v63, v63
	v_mul_f32_e32 v48, v48, v56
	v_mul_f32_e32 v49, v49, v57
	v_mul_f32_e32 v50, v50, v58
	v_mul_f32_e32 v51, v51, v59
	s_waitcnt lgkmcnt(0)
	v_mfma_f32_32x32x16_bf16 v[234:249], v[108:111], v[208:211], v[234:249]
	v_mul_f32_e32 v52, v52, v60
	v_mul_f32_e32 v53, v53, v61
	v_mul_f32_e32 v54, v54, v62
	v_mul_f32_e32 v55, v55, v63
	v_cvt_pk_bf16_f32 v56, v48, v49
	v_cvt_pk_bf16_f32 v57, v50, v51
	v_cvt_pk_bf16_f32 v58, v52, v53
	v_cvt_pk_bf16_f32 v59, v54, v55
	global_store_dwordx2 v253, v[56:57], s[14:15]
	global_store_dwordx2 v254, v[58:59], s[14:15]
	s_movk_i32 s18, 0x1000
	s_and_b32 s17, s16, 0x3800
	s_cmp_eq_u32 s17, 0x800
	s_cselect_b32 s18, 0x1f9000, s18
	s_add_u32 s14, s14, s18
	s_addc_u32 s15, s15, 0
	s_cmp_lt_u32 s16, 0x2800
	s_cbranch_scc1 .Lscan_w3_2
	s_waitcnt vmcnt(11)
.Lscan_go_2:
	v_mfma_f32_32x32x16_bf16 v[0:15], v[156:159], v[104:107], 0
	s_addk_i32 s16, 0x800
	v_mfma_f32_32x32x16_bf16 v[16:31], v[156:159], v[116:119], 0
	v_mfma_f32_32x32x16_bf16 v[32:47], v[156:159], v[92:95], 0
	v_mfma_f32_32x32x16_bf16 v[196:211], v[156:159], v[112:115], 0
	v_mov_b32_e32 v218, v156
	v_mov_b32_e32 v219, v157
	v_mov_b32_e32 v220, v158
	v_mov_b32_e32 v221, v159
	s_nop 0
	v_permlane32_swap_b32_e32 v218, v220
	v_permlane32_swap_b32_e32 v219, v221
	s_add_u32 s0, s0, 0x40000
	s_addc_u32 s1, s1, 0
	v_lshl_add_u64 v[216:217], v[152:153], 0, s[0:1]
	global_load_dwordx4 v[156:159], v[216:217], off
	v_lshlrev_b32_e32 v228, 16, v218
	v_and_b32_e32 v229, 0xffff0000, v218
	v_lshlrev_b32_e32 v230, 16, v219
	v_and_b32_e32 v231, 0xffff0000, v219
	v_lshlrev_b32_e32 v232, 16, v220
	v_and_b32_e32 v233, 0xffff0000, v220
	v_lshlrev_b32_e32 v251, 16, v221
	v_and_b32_e32 v252, 0xffff0000, v221
	v_permlane32_swap_b32_e32 v0, v16
	v_permlane32_swap_b32_e32 v1, v17
	v_permlane32_swap_b32_e32 v2, v18
	v_permlane32_swap_b32_e32 v3, v19
	v_permlane32_swap_b32_e32 v4, v20
	v_permlane32_swap_b32_e32 v5, v21
	v_permlane32_swap_b32_e32 v6, v22
	v_permlane32_swap_b32_e32 v7, v23
	v_permlane32_swap_b32_e32 v8, v24
	v_permlane32_swap_b32_e32 v9, v25
	v_permlane32_swap_b32_e32 v10, v26
	v_permlane32_swap_b32_e32 v11, v27
	v_permlane32_swap_b32_e32 v12, v28
	v_permlane32_swap_b32_e32 v13, v29
	v_permlane32_swap_b32_e32 v14, v30
	v_permlane32_swap_b32_e32 v15, v31
	v_permlane32_swap_b32_e32 v32, v196
	v_permlane32_swap_b32_e32 v33, v197
	v_permlane32_swap_b32_e32 v34, v198
	v_permlane32_swap_b32_e32 v35, v199
	v_permlane32_swap_b32_e32 v36, v200
	v_permlane32_swap_b32_e32 v37, v201
	v_permlane32_swap_b32_e32 v38, v202
	v_permlane32_swap_b32_e32 v39, v203
	v_permlane32_swap_b32_e32 v40, v204
	v_permlane32_swap_b32_e32 v41, v205
	v_permlane32_swap_b32_e32 v42, v206
	v_permlane32_swap_b32_e32 v43, v207
	v_permlane32_swap_b32_e32 v44, v208
	v_permlane32_swap_b32_e32 v45, v209
	v_permlane32_swap_b32_e32 v46, v210
	v_permlane32_swap_b32_e32 v47, v211
	v_fmac_f32_e32 v0, v160, v188
	v_fmac_f32_e32 v32, v160, v189
	v_fma_f32 v0, -v161, v189, v0
	v_fmac_f32_e32 v32, v161, v188
	v_fmac_f32_e32 v1, v160, v0
	v_fmac_f32_e32 v33, v160, v32
	v_cvt_pk_bf16_f32 v212, v0, v32
	v_fma_f32 v1, -v161, v32, v1
	v_fmac_f32_e32 v33, v161, v0
	v_fmac_f32_e32 v2, v160, v1
	v_fmac_f32_e32 v34, v160, v33
	v_cvt_pk_bf16_f32 v213, v1, v33
	v_fma_f32 v2, -v161, v33, v2
	v_fmac_f32_e32 v34, v161, v1
	ds_write2_b32 v222, v212, v213 offset0:0 offset1:68
	v_fmac_f32_e32 v3, v160, v2
	v_fmac_f32_e32 v35, v160, v34
	v_cvt_pk_bf16_f32 v214, v2, v34
	v_fma_f32 v3, -v161, v34, v3
	v_fmac_f32_e32 v35, v161, v2
	v_fmac_f32_e32 v16, v160, v3
	v_fmac_f32_e32 v196, v160, v35
	v_cvt_pk_bf16_f32 v215, v3, v35
	v_fma_f32 v16, -v161, v35, v16
	v_fmac_f32_e32 v196, v161, v3
	ds_write2_b32 v222, v214, v215 offset0:136 offset1:204
	v_fmac_f32_e32 v17, v160, v16
	v_fmac_f32_e32 v197, v160, v196
	v_cvt_pk_bf16_f32 v212, v16, v196
	v_fma_f32 v17, -v161, v196, v17
	v_fmac_f32_e32 v197, v161, v16
	v_fmac_f32_e32 v18, v160, v17
	v_fmac_f32_e32 v198, v160, v197
	v_cvt_pk_bf16_f32 v213, v17, v197
	v_fma_f32 v18, -v161, v197, v18
	v_fmac_f32_e32 v198, v161, v17
	ds_write2_b32 v223, v212, v213 offset0:0 offset1:68
	v_fmac_f32_e32 v19, v160, v18
	v_fmac_f32_e32 v199, v160, v198
	v_cvt_pk_bf16_f32 v214, v18, v198
	v_fma_f32 v19, -v161, v198, v19
	v_fmac_f32_e32 v199, v161, v18
	v_fmac_f32_e32 v4, v160, v19
	v_fmac_f32_e32 v36, v160, v199
	v_cvt_pk_bf16_f32 v215, v19, v199
	v_fma_f32 v4, -v161, v199, v4
	v_fmac_f32_e32 v36, v161, v19
	ds_write2_b32 v223, v214, v215 offset0:136 offset1:204
	v_fmac_f32_e32 v5, v160, v4
	v_fmac_f32_e32 v37, v160, v36
	v_cvt_pk_bf16_f32 v212, v4, v36
	v_fma_f32 v5, -v161, v36, v5
	v_fmac_f32_e32 v37, v161, v4
	v_fmac_f32_e32 v6, v160, v5
	v_fmac_f32_e32 v38, v160, v37
	v_cvt_pk_bf16_f32 v213, v5, v37
	v_fma_f32 v6, -v161, v37, v6
	v_fmac_f32_e32 v38, v161, v5
	ds_write2_b32 v224, v212, v213 offset0:0 offset1:68
	v_fmac_f32_e32 v7, v160, v6
	v_fmac_f32_e32 v39, v160, v38
	v_cvt_pk_bf16_f32 v214, v6, v38
	v_fma_f32 v7, -v161, v38, v7
	v_fmac_f32_e32 v39, v161, v6
	v_fmac_f32_e32 v20, v160, v7
	v_fmac_f32_e32 v200, v160, v39
	v_cvt_pk_bf16_f32 v215, v7, v39
	v_fma_f32 v20, -v161, v39, v20
	v_fmac_f32_e32 v200, v161, v7
	ds_write2_b32 v224, v214, v215 offset0:136 offset1:204
	v_fmac_f32_e32 v21, v160, v20
	v_fmac_f32_e32 v201, v160, v200
	v_cvt_pk_bf16_f32 v212, v20, v200
	v_fma_f32 v21, -v161, v200, v21
	v_fmac_f32_e32 v201, v161, v20
	v_fmac_f32_e32 v22, v160, v21
	v_fmac_f32_e32 v202, v160, v201
	v_cvt_pk_bf16_f32 v213, v21, v201
	v_fma_f32 v22, -v161, v201, v22
	v_fmac_f32_e32 v202, v161, v21
	ds_write2_b32 v225, v212, v213 offset0:0 offset1:68
	v_fmac_f32_e32 v23, v160, v22
	v_fmac_f32_e32 v203, v160, v202
	v_cvt_pk_bf16_f32 v214, v22, v202
	v_fma_f32 v23, -v161, v202, v23
	v_fmac_f32_e32 v203, v161, v22
	v_fmac_f32_e32 v8, v160, v23
	v_fmac_f32_e32 v40, v160, v203
	v_cvt_pk_bf16_f32 v215, v23, v203
	v_fma_f32 v8, -v161, v203, v8
	v_fmac_f32_e32 v40, v161, v23
	ds_write2_b32 v225, v214, v215 offset0:136 offset1:204
	v_fmac_f32_e32 v9, v160, v8
	v_fmac_f32_e32 v41, v160, v40
	v_cvt_pk_bf16_f32 v212, v8, v40
	v_fma_f32 v9, -v161, v40, v9
	v_fmac_f32_e32 v41, v161, v8
	v_fmac_f32_e32 v10, v160, v9
	v_fmac_f32_e32 v42, v160, v41
	v_cvt_pk_bf16_f32 v213, v9, v41
	v_fma_f32 v10, -v161, v41, v10
	v_fmac_f32_e32 v42, v161, v9
	ds_write2_b32 v226, v212, v213 offset0:0 offset1:68
	v_fmac_f32_e32 v11, v160, v10
	v_fmac_f32_e32 v43, v160, v42
	v_cvt_pk_bf16_f32 v214, v10, v42
	v_fma_f32 v11, -v161, v42, v11
	v_fmac_f32_e32 v43, v161, v10
	v_fmac_f32_e32 v24, v160, v11
	v_fmac_f32_e32 v204, v160, v43
	v_cvt_pk_bf16_f32 v215, v11, v43
	v_fma_f32 v24, -v161, v43, v24
	v_fmac_f32_e32 v204, v161, v11
	ds_write2_b32 v226, v214, v215 offset0:136 offset1:204
	v_fmac_f32_e32 v25, v160, v24
	v_fmac_f32_e32 v205, v160, v204
	v_cvt_pk_bf16_f32 v212, v24, v204
	v_fma_f32 v25, -v161, v204, v25
	v_fmac_f32_e32 v205, v161, v24
	v_fmac_f32_e32 v26, v160, v25
	v_fmac_f32_e32 v206, v160, v205
	v_cvt_pk_bf16_f32 v213, v25, v205
	v_fma_f32 v26, -v161, v205, v26
	v_fmac_f32_e32 v206, v161, v25
	ds_write2_b32 v227, v212, v213 offset0:0 offset1:68
	v_fmac_f32_e32 v27, v160, v26
	v_fmac_f32_e32 v207, v160, v206
	v_cvt_pk_bf16_f32 v214, v26, v206
	v_fma_f32 v27, -v161, v206, v27
	v_fmac_f32_e32 v207, v161, v26
	v_fmac_f32_e32 v12, v160, v27
	v_fmac_f32_e32 v44, v160, v207
	v_cvt_pk_bf16_f32 v215, v27, v207
	v_fma_f32 v12, -v161, v207, v12
	v_fmac_f32_e32 v44, v161, v27
	ds_write2_b32 v227, v214, v215 offset0:136 offset1:204
	v_fmac_f32_e32 v13, v160, v12
	v_fmac_f32_e32 v45, v160, v44
	v_cvt_pk_bf16_f32 v212, v12, v44
	v_fma_f32 v13, -v161, v44, v13
	v_fmac_f32_e32 v45, v161, v12
	v_fmac_f32_e32 v14, v160, v13
	v_fmac_f32_e32 v46, v160, v45
	v_cvt_pk_bf16_f32 v213, v13, v45
	v_fma_f32 v14, -v161, v45, v14
	v_fmac_f32_e32 v46, v161, v13
	ds_write2_b32 v190, v212, v213 offset0:0 offset1:68
	v_fmac_f32_e32 v15, v160, v14
	v_fmac_f32_e32 v47, v160, v46
	v_cvt_pk_bf16_f32 v214, v14, v46
	v_fma_f32 v15, -v161, v46, v15
	v_fmac_f32_e32 v47, v161, v14
	v_fmac_f32_e32 v28, v160, v15
	v_fmac_f32_e32 v208, v160, v47
	v_cvt_pk_bf16_f32 v215, v15, v47
	v_fma_f32 v28, -v161, v47, v28
	v_fmac_f32_e32 v208, v161, v15
	ds_write2_b32 v190, v214, v215 offset0:136 offset1:204
	v_fmac_f32_e32 v29, v160, v28
	v_fmac_f32_e32 v209, v160, v208
	v_cvt_pk_bf16_f32 v212, v28, v208
	v_fma_f32 v29, -v161, v208, v29
	v_fmac_f32_e32 v209, v161, v28
	v_fmac_f32_e32 v30, v160, v29
	v_fmac_f32_e32 v210, v160, v209
	v_cvt_pk_bf16_f32 v213, v29, v209
	v_fma_f32 v30, -v161, v209, v30
	v_fmac_f32_e32 v210, v161, v29
	ds_write2_b32 v191, v212, v213 offset0:0 offset1:68
	v_fmac_f32_e32 v31, v160, v30
	v_fmac_f32_e32 v211, v160, v210
	v_cvt_pk_bf16_f32 v214, v30, v210
	v_fma_f32 v31, -v161, v210, v31
	v_fmac_f32_e32 v211, v161, v30
	v_mov_b32_e32 v188, v31
	v_mov_b32_e32 v189, v211
	v_cvt_pk_bf16_f32 v215, v31, v211
	ds_write2_b32 v191, v214, v215 offset0:136 offset1:204
	s_waitcnt lgkmcnt(0)
	ds_read_b128 v[32:35], v186 offset:18432
	ds_read_b128 v[36:39], v186 offset:18464
	ds_read_b128 v[40:43], v186 offset:18496
	ds_read_b128 v[44:47], v186 offset:18528
	ds_read_b128 v[196:199], v186 offset:18560
	ds_read_b128 v[200:203], v186 offset:18592
	ds_read_b128 v[204:207], v186 offset:18624
	ds_read_b128 v[208:211], v186 offset:18656
	s_waitcnt lgkmcnt(7)
	v_mfma_f32_32x32x16_bf16 v[48:63], v[64:67], v[32:35], 0
	v_fmac_f32_e32 v234, v100, v162
	v_fmac_f32_e32 v235, v101, v163
	v_fmac_f32_e32 v236, v102, v164
	v_fmac_f32_e32 v237, v103, v165
	v_fmac_f32_e32 v238, v80, v166
	v_fmac_f32_e32 v239, v81, v167
	v_fmac_f32_e32 v240, v82, v192
	v_fmac_f32_e32 v241, v83, v193
	v_mul_f32_e32 v242, v234, v234
	s_waitcnt lgkmcnt(6)
	v_mfma_f32_32x32x16_bf16 v[48:63], v[68:71], v[36:39], v[48:63]
	v_mul_f32_e32 v243, v235, v235
	v_mul_f32_e32 v244, v236, v236
	v_mul_f32_e32 v245, v237, v237
	v_mul_f32_e32 v246, v238, v238
	v_mul_f32_e32 v247, v239, v239
	v_mul_f32_e32 v248, v240, v240
	v_mul_f32_e32 v249, v241, v241
	v_fmaak_f32 v242, v242, v184, 0xc0135761
	v_fmaak_f32 v243, v243, v184, 0xc0135761
	s_waitcnt lgkmcnt(5)
	v_mfma_f32_32x32x16_bf16 v[48:63], v[72:75], v[40:43], v[48:63]
	v_fmaak_f32 v244, v244, v184, 0xc0135761
	v_fmaak_f32 v245, v245, v184, 0xc0135761
	v_fmaak_f32 v246, v246, v184, 0xc0135761
	v_fmaak_f32 v247, v247, v184, 0xc0135761
	v_fmaak_f32 v248, v248, v184, 0xc0135761
	v_fmaak_f32 v249, v249, v184, 0xc0135761
	v_mul_f32_e32 v242, v234, v242
	v_mul_f32_e32 v243, v235, v243
	v_mul_f32_e32 v244, v236, v244
	s_waitcnt lgkmcnt(4)
	v_mfma_f32_32x32x16_bf16 v[48:63], v[76:79], v[44:47], v[48:63]
	v_mul_f32_e32 v245, v237, v245
	v_mul_f32_e32 v246, v238, v246
	v_mul_f32_e32 v247, v239, v247
	v_mul_f32_e32 v248, v240, v248
	v_mul_f32_e32 v249, v241, v249
	v_exp_f32_e32 v242, v242
	v_exp_f32_e32 v243, v243
	v_exp_f32_e32 v244, v244
	v_exp_f32_e32 v245, v245
	s_waitcnt lgkmcnt(3)
	v_mfma_f32_32x32x16_bf16 v[48:63], v[84:87], v[196:199], v[48:63]
	v_exp_f32_e32 v246, v246
	v_exp_f32_e32 v247, v247
	v_exp_f32_e32 v248, v248
	v_exp_f32_e32 v249, v249
	v_add_f32_e32 v242, 1.0, v242
	v_add_f32_e32 v243, 1.0, v243
	v_add_f32_e32 v244, 1.0, v244
	v_add_f32_e32 v245, 1.0, v245
	s_waitcnt lgkmcnt(2)
	v_mfma_f32_32x32x16_bf16 v[48:63], v[88:91], v[200:203], v[48:63]
	v_add_f32_e32 v246, 1.0, v246
	v_add_f32_e32 v247, 1.0, v247
	v_add_f32_e32 v248, 1.0, v248
	v_add_f32_e32 v249, 1.0, v249
	v_rcp_f32_e32 v242, v242
	v_rcp_f32_e32 v243, v243
	v_rcp_f32_e32 v244, v244
	v_rcp_f32_e32 v245, v245
	s_waitcnt lgkmcnt(1)
	v_mfma_f32_32x32x16_bf16 v[48:63], v[96:99], v[204:207], v[48:63]
	v_rcp_f32_e32 v246, v246
	v_rcp_f32_e32 v247, v247
	v_rcp_f32_e32 v248, v248
	v_rcp_f32_e32 v249, v249
	v_mul_f32_e32 v234, v234, v242
	v_mul_f32_e32 v235, v235, v243
	v_mul_f32_e32 v236, v236, v244
	v_mul_f32_e32 v237, v237, v245
	s_waitcnt lgkmcnt(0)
	v_mfma_f32_32x32x16_bf16 v[48:63], v[108:111], v[208:211], v[48:63]
	v_mul_f32_e32 v238, v238, v246
	v_mul_f32_e32 v239, v239, v247
	v_mul_f32_e32 v240, v240, v248
	v_mul_f32_e32 v241, v241, v249
	v_cvt_pk_bf16_f32 v242, v234, v235
	v_cvt_pk_bf16_f32 v243, v236, v237
	v_cvt_pk_bf16_f32 v244, v238, v239
	v_cvt_pk_bf16_f32 v245, v240, v241
	global_store_dwordx2 v253, v[242:243], s[14:15]
	global_store_dwordx2 v254, v[244:245], s[14:15]
	s_movk_i32 s18, 0x1000
	s_and_b32 s17, s16, 0x3800
	s_cmp_eq_u32 s17, 0x800
	s_cselect_b32 s18, 0x1f9000, s18
	s_add_u32 s14, s14, s18
	s_addc_u32 s15, s15, 0
	s_cmp_lt_u32 s16, 0x2800
	s_cbranch_scc1 .Lscan_w3_3
	s_waitcnt vmcnt(11)
.Lscan_go_3:
	v_mfma_f32_32x32x16_bf16 v[0:15], v[178:181], v[104:107], 0
	s_addk_i32 s16, 0x800
	v_mfma_f32_32x32x16_bf16 v[16:31], v[178:181], v[116:119], 0
	v_mfma_f32_32x32x16_bf16 v[32:47], v[178:181], v[92:95], 0
	v_mfma_f32_32x32x16_bf16 v[196:211], v[178:181], v[112:115], 0
	v_mov_b32_e32 v218, v178
	v_mov_b32_e32 v219, v179
	v_mov_b32_e32 v220, v180
	v_mov_b32_e32 v221, v181
	s_nop 0
	v_permlane32_swap_b32_e32 v218, v220
	v_permlane32_swap_b32_e32 v219, v221
	s_add_u32 s0, s0, 0x40000
	s_addc_u32 s1, s1, 0
	v_lshl_add_u64 v[216:217], v[152:153], 0, s[0:1]
	global_load_dwordx4 v[178:181], v[216:217], off
	v_lshlrev_b32_e32 v162, 16, v218
	v_and_b32_e32 v163, 0xffff0000, v218
	v_lshlrev_b32_e32 v164, 16, v219
	v_and_b32_e32 v165, 0xffff0000, v219
	v_lshlrev_b32_e32 v166, 16, v220
	v_and_b32_e32 v167, 0xffff0000, v220
	v_lshlrev_b32_e32 v192, 16, v221
	v_and_b32_e32 v193, 0xffff0000, v221
	v_permlane32_swap_b32_e32 v0, v16
	v_permlane32_swap_b32_e32 v1, v17
	v_permlane32_swap_b32_e32 v2, v18
	v_permlane32_swap_b32_e32 v3, v19
	v_permlane32_swap_b32_e32 v4, v20
	v_permlane32_swap_b32_e32 v5, v21
	v_permlane32_swap_b32_e32 v6, v22
	v_permlane32_swap_b32_e32 v7, v23
	v_permlane32_swap_b32_e32 v8, v24
	v_permlane32_swap_b32_e32 v9, v25
	v_permlane32_swap_b32_e32 v10, v26
	v_permlane32_swap_b32_e32 v11, v27
	v_permlane32_swap_b32_e32 v12, v28
	v_permlane32_swap_b32_e32 v13, v29
	v_permlane32_swap_b32_e32 v14, v30
	v_permlane32_swap_b32_e32 v15, v31
	v_permlane32_swap_b32_e32 v32, v196
	v_permlane32_swap_b32_e32 v33, v197
	v_permlane32_swap_b32_e32 v34, v198
	v_permlane32_swap_b32_e32 v35, v199
	v_permlane32_swap_b32_e32 v36, v200
	v_permlane32_swap_b32_e32 v37, v201
	v_permlane32_swap_b32_e32 v38, v202
	v_permlane32_swap_b32_e32 v39, v203
	v_permlane32_swap_b32_e32 v40, v204
	v_permlane32_swap_b32_e32 v41, v205
	v_permlane32_swap_b32_e32 v42, v206
	v_permlane32_swap_b32_e32 v43, v207
	v_permlane32_swap_b32_e32 v44, v208
	v_permlane32_swap_b32_e32 v45, v209
	v_permlane32_swap_b32_e32 v46, v210
	v_permlane32_swap_b32_e32 v47, v211
	v_fmac_f32_e32 v0, v160, v188
	v_fmac_f32_e32 v32, v160, v189
	v_fma_f32 v0, -v161, v189, v0
	v_fmac_f32_e32 v32, v161, v188
	v_fmac_f32_e32 v1, v160, v0
	v_fmac_f32_e32 v33, v160, v32
	v_cvt_pk_bf16_f32 v212, v0, v32
	v_fma_f32 v1, -v161, v32, v1
	v_fmac_f32_e32 v33, v161, v0
	v_fmac_f32_e32 v2, v160, v1
	v_fmac_f32_e32 v34, v160, v33
	v_cvt_pk_bf16_f32 v213, v1, v33
	v_fma_f32 v2, -v161, v33, v2
	v_fmac_f32_e32 v34, v161, v1
	ds_write2_b32 v222, v212, v213 offset0:0 offset1:68
	v_fmac_f32_e32 v3, v160, v2
	v_fmac_f32_e32 v35, v160, v34
	v_cvt_pk_bf16_f32 v214, v2, v34
	v_fma_f32 v3, -v161, v34, v3
	v_fmac_f32_e32 v35, v161, v2
	v_fmac_f32_e32 v16, v160, v3
	v_fmac_f32_e32 v196, v160, v35
	v_cvt_pk_bf16_f32 v215, v3, v35
	v_fma_f32 v16, -v161, v35, v16
	v_fmac_f32_e32 v196, v161, v3
	ds_write2_b32 v222, v214, v215 offset0:136 offset1:204
	v_fmac_f32_e32 v17, v160, v16
	v_fmac_f32_e32 v197, v160, v196
	v_cvt_pk_bf16_f32 v212, v16, v196
	v_fma_f32 v17, -v161, v196, v17
	v_fmac_f32_e32 v197, v161, v16
	v_fmac_f32_e32 v18, v160, v17
	v_fmac_f32_e32 v198, v160, v197
	v_cvt_pk_bf16_f32 v213, v17, v197
	v_fma_f32 v18, -v161, v197, v18
	v_fmac_f32_e32 v198, v161, v17
	ds_write2_b32 v223, v212, v213 offset0:0 offset1:68
	v_fmac_f32_e32 v19, v160, v18
	v_fmac_f32_e32 v199, v160, v198
	v_cvt_pk_bf16_f32 v214, v18, v198
	v_fma_f32 v19, -v161, v198, v19
	v_fmac_f32_e32 v199, v161, v18
	v_fmac_f32_e32 v4, v160, v19
	v_fmac_f32_e32 v36, v160, v199
	v_cvt_pk_bf16_f32 v215, v19, v199
	v_fma_f32 v4, -v161, v199, v4
	v_fmac_f32_e32 v36, v161, v19
	ds_write2_b32 v223, v214, v215 offset0:136 offset1:204
	v_fmac_f32_e32 v5, v160, v4
	v_fmac_f32_e32 v37, v160, v36
	v_cvt_pk_bf16_f32 v212, v4, v36
	v_fma_f32 v5, -v161, v36, v5
	v_fmac_f32_e32 v37, v161, v4
	v_fmac_f32_e32 v6, v160, v5
	v_fmac_f32_e32 v38, v160, v37
	v_cvt_pk_bf16_f32 v213, v5, v37
	v_fma_f32 v6, -v161, v37, v6
	v_fmac_f32_e32 v38, v161, v5
	ds_write2_b32 v224, v212, v213 offset0:0 offset1:68
	v_fmac_f32_e32 v7, v160, v6
	v_fmac_f32_e32 v39, v160, v38
	v_cvt_pk_bf16_f32 v214, v6, v38
	v_fma_f32 v7, -v161, v38, v7
	v_fmac_f32_e32 v39, v161, v6
	v_fmac_f32_e32 v20, v160, v7
	v_fmac_f32_e32 v200, v160, v39
	v_cvt_pk_bf16_f32 v215, v7, v39
	v_fma_f32 v20, -v161, v39, v20
	v_fmac_f32_e32 v200, v161, v7
	ds_write2_b32 v224, v214, v215 offset0:136 offset1:204
	v_fmac_f32_e32 v21, v160, v20
	v_fmac_f32_e32 v201, v160, v200
	v_cvt_pk_bf16_f32 v212, v20, v200
	v_fma_f32 v21, -v161, v200, v21
	v_fmac_f32_e32 v201, v161, v20
	v_fmac_f32_e32 v22, v160, v21
	v_fmac_f32_e32 v202, v160, v201
	v_cvt_pk_bf16_f32 v213, v21, v201
	v_fma_f32 v22, -v161, v201, v22
	v_fmac_f32_e32 v202, v161, v21
	ds_write2_b32 v225, v212, v213 offset0:0 offset1:68
	v_fmac_f32_e32 v23, v160, v22
	v_fmac_f32_e32 v203, v160, v202
	v_cvt_pk_bf16_f32 v214, v22, v202
	v_fma_f32 v23, -v161, v202, v23
	v_fmac_f32_e32 v203, v161, v22
	v_fmac_f32_e32 v8, v160, v23
	v_fmac_f32_e32 v40, v160, v203
	v_cvt_pk_bf16_f32 v215, v23, v203
	v_fma_f32 v8, -v161, v203, v8
	v_fmac_f32_e32 v40, v161, v23
	ds_write2_b32 v225, v214, v215 offset0:136 offset1:204
	v_fmac_f32_e32 v9, v160, v8
	v_fmac_f32_e32 v41, v160, v40
	v_cvt_pk_bf16_f32 v212, v8, v40
	v_fma_f32 v9, -v161, v40, v9
	v_fmac_f32_e32 v41, v161, v8
	v_fmac_f32_e32 v10, v160, v9
	v_fmac_f32_e32 v42, v160, v41
	v_cvt_pk_bf16_f32 v213, v9, v41
	v_fma_f32 v10, -v161, v41, v10
	v_fmac_f32_e32 v42, v161, v9
	ds_write2_b32 v226, v212, v213 offset0:0 offset1:68
	v_fmac_f32_e32 v11, v160, v10
	v_fmac_f32_e32 v43, v160, v42
	v_cvt_pk_bf16_f32 v214, v10, v42
	v_fma_f32 v11, -v161, v42, v11
	v_fmac_f32_e32 v43, v161, v10
	v_fmac_f32_e32 v24, v160, v11
	v_fmac_f32_e32 v204, v160, v43
	v_cvt_pk_bf16_f32 v215, v11, v43
	v_fma_f32 v24, -v161, v43, v24
	v_fmac_f32_e32 v204, v161, v11
	ds_write2_b32 v226, v214, v215 offset0:136 offset1:204
	v_fmac_f32_e32 v25, v160, v24
	v_fmac_f32_e32 v205, v160, v204
	v_cvt_pk_bf16_f32 v212, v24, v204
	v_fma_f32 v25, -v161, v204, v25
	v_fmac_f32_e32 v205, v161, v24
	v_fmac_f32_e32 v26, v160, v25
	v_fmac_f32_e32 v206, v160, v205
	v_cvt_pk_bf16_f32 v213, v25, v205
	v_fma_f32 v26, -v161, v205, v26
	v_fmac_f32_e32 v206, v161, v25
	ds_write2_b32 v227, v212, v213 offset0:0 offset1:68
	v_fmac_f32_e32 v27, v160, v26
	v_fmac_f32_e32 v207, v160, v206
	v_cvt_pk_bf16_f32 v214, v26, v206
	v_fma_f32 v27, -v161, v206, v27
	v_fmac_f32_e32 v207, v161, v26
	v_fmac_f32_e32 v12, v160, v27
	v_fmac_f32_e32 v44, v160, v207
	v_cvt_pk_bf16_f32 v215, v27, v207
	v_fma_f32 v12, -v161, v207, v12
	v_fmac_f32_e32 v44, v161, v27
	ds_write2_b32 v227, v214, v215 offset0:136 offset1:204
	v_fmac_f32_e32 v13, v160, v12
	v_fmac_f32_e32 v45, v160, v44
	v_cvt_pk_bf16_f32 v212, v12, v44
	v_fma_f32 v13, -v161, v44, v13
	v_fmac_f32_e32 v45, v161, v12
	v_fmac_f32_e32 v14, v160, v13
	v_fmac_f32_e32 v46, v160, v45
	v_cvt_pk_bf16_f32 v213, v13, v45
	v_fma_f32 v14, -v161, v45, v14
	v_fmac_f32_e32 v46, v161, v13
	ds_write2_b32 v190, v212, v213 offset0:0 offset1:68
	v_fmac_f32_e32 v15, v160, v14
	v_fmac_f32_e32 v47, v160, v46
	v_cvt_pk_bf16_f32 v214, v14, v46
	v_fma_f32 v15, -v161, v46, v15
	v_fmac_f32_e32 v47, v161, v14
	v_fmac_f32_e32 v28, v160, v15
	v_fmac_f32_e32 v208, v160, v47
	v_cvt_pk_bf16_f32 v215, v15, v47
	v_fma_f32 v28, -v161, v47, v28
	v_fmac_f32_e32 v208, v161, v15
	ds_write2_b32 v190, v214, v215 offset0:136 offset1:204
	v_fmac_f32_e32 v29, v160, v28
	v_fmac_f32_e32 v209, v160, v208
	v_cvt_pk_bf16_f32 v212, v28, v208
	v_fma_f32 v29, -v161, v208, v29
	v_fmac_f32_e32 v209, v161, v28
	v_fmac_f32_e32 v30, v160, v29
	v_fmac_f32_e32 v210, v160, v209
	v_cvt_pk_bf16_f32 v213, v29, v209
	v_fma_f32 v30, -v161, v209, v30
	v_fmac_f32_e32 v210, v161, v29
	ds_write2_b32 v191, v212, v213 offset0:0 offset1:68
	v_fmac_f32_e32 v31, v160, v30
	v_fmac_f32_e32 v211, v160, v210
	v_cvt_pk_bf16_f32 v214, v30, v210
	v_fma_f32 v31, -v161, v210, v31
	v_fmac_f32_e32 v211, v161, v30
	v_mov_b32_e32 v188, v31
	v_mov_b32_e32 v189, v211
	v_cvt_pk_bf16_f32 v215, v31, v211
	ds_write2_b32 v191, v214, v215 offset0:136 offset1:204
	s_waitcnt lgkmcnt(0)
	ds_read_b128 v[32:35], v186 offset:18432
	ds_read_b128 v[36:39], v186 offset:18464
	ds_read_b128 v[40:43], v186 offset:18496
	ds_read_b128 v[44:47], v186 offset:18528
	ds_read_b128 v[196:199], v186 offset:18560
	ds_read_b128 v[200:203], v186 offset:18592
	ds_read_b128 v[204:207], v186 offset:18624
	ds_read_b128 v[208:211], v186 offset:18656
	s_waitcnt lgkmcnt(7)
	v_mfma_f32_32x32x16_bf16 v[234:249], v[64:67], v[32:35], 0
	v_fmac_f32_e32 v48, v100, v228
	v_fmac_f32_e32 v49, v101, v229
	v_fmac_f32_e32 v50, v102, v230
	v_fmac_f32_e32 v51, v103, v231
	v_fmac_f32_e32 v52, v80, v232
	v_fmac_f32_e32 v53, v81, v233
	v_fmac_f32_e32 v54, v82, v251
	v_fmac_f32_e32 v55, v83, v252
	v_mul_f32_e32 v56, v48, v48
	s_waitcnt lgkmcnt(6)
	v_mfma_f32_32x32x16_bf16 v[234:249], v[68:71], v[36:39], v[234:249]
	v_mul_f32_e32 v57, v49, v49
	v_mul_f32_e32 v58, v50, v50
	v_mul_f32_e32 v59, v51, v51
	v_mul_f32_e32 v60, v52, v52
	v_mul_f32_e32 v61, v53, v53
	v_mul_f32_e32 v62, v54, v54
	v_mul_f32_e32 v63, v55, v55
	v_fmaak_f32 v56, v56, v184, 0xc0135761
	v_fmaak_f32 v57, v57, v184, 0xc0135761
	s_waitcnt lgkmcnt(5)
	v_mfma_f32_32x32x16_bf16 v[234:249], v[72:75], v[40:43], v[234:249]
	v_fmaak_f32 v58, v58, v184, 0xc0135761
	v_fmaak_f32 v59, v59, v184, 0xc0135761
	v_fmaak_f32 v60, v60, v184, 0xc0135761
	v_fmaak_f32 v61, v61, v184, 0xc0135761
	v_fmaak_f32 v62, v62, v184, 0xc0135761
	v_fmaak_f32 v63, v63, v184, 0xc0135761
	v_mul_f32_e32 v56, v48, v56
	v_mul_f32_e32 v57, v49, v57
	v_mul_f32_e32 v58, v50, v58
	s_waitcnt lgkmcnt(4)
	v_mfma_f32_32x32x16_bf16 v[234:249], v[76:79], v[44:47], v[234:249]
	v_mul_f32_e32 v59, v51, v59
	v_mul_f32_e32 v60, v52, v60
	v_mul_f32_e32 v61, v53, v61
	v_mul_f32_e32 v62, v54, v62
	v_mul_f32_e32 v63, v55, v63
	v_exp_f32_e32 v56, v56
	v_exp_f32_e32 v57, v57
	v_exp_f32_e32 v58, v58
	v_exp_f32_e32 v59, v59
	s_waitcnt lgkmcnt(3)
	v_mfma_f32_32x32x16_bf16 v[234:249], v[84:87], v[196:199], v[234:249]
	v_exp_f32_e32 v60, v60
	v_exp_f32_e32 v61, v61
	v_exp_f32_e32 v62, v62
	v_exp_f32_e32 v63, v63
	v_add_f32_e32 v56, 1.0, v56
	v_add_f32_e32 v57, 1.0, v57
	v_add_f32_e32 v58, 1.0, v58
	v_add_f32_e32 v59, 1.0, v59
	s_waitcnt lgkmcnt(2)
	v_mfma_f32_32x32x16_bf16 v[234:249], v[88:91], v[200:203], v[234:249]
	v_add_f32_e32 v60, 1.0, v60
	v_add_f32_e32 v61, 1.0, v61
	v_add_f32_e32 v62, 1.0, v62
	v_add_f32_e32 v63, 1.0, v63
	v_rcp_f32_e32 v56, v56
	v_rcp_f32_e32 v57, v57
	v_rcp_f32_e32 v58, v58
	v_rcp_f32_e32 v59, v59
	s_waitcnt lgkmcnt(1)
	v_mfma_f32_32x32x16_bf16 v[234:249], v[96:99], v[204:207], v[234:249]
	v_rcp_f32_e32 v60, v60
	v_rcp_f32_e32 v61, v61
	v_rcp_f32_e32 v62, v62
	v_rcp_f32_e32 v63, v63
	v_mul_f32_e32 v48, v48, v56
	v_mul_f32_e32 v49, v49, v57
	v_mul_f32_e32 v50, v50, v58
	v_mul_f32_e32 v51, v51, v59
	s_waitcnt lgkmcnt(0)
	v_mfma_f32_32x32x16_bf16 v[234:249], v[108:111], v[208:211], v[234:249]
	v_mul_f32_e32 v52, v52, v60
	v_mul_f32_e32 v53, v53, v61
	v_mul_f32_e32 v54, v54, v62
	v_mul_f32_e32 v55, v55, v63
	v_cvt_pk_bf16_f32 v56, v48, v49
	v_cvt_pk_bf16_f32 v57, v50, v51
	v_cvt_pk_bf16_f32 v58, v52, v53
	v_cvt_pk_bf16_f32 v59, v54, v55
	global_store_dwordx2 v253, v[56:57], s[14:15]
	global_store_dwordx2 v254, v[58:59], s[14:15]
	s_movk_i32 s18, 0x1000
	s_and_b32 s17, s16, 0x3800
	s_cmp_eq_u32 s17, 0x800
	s_cselect_b32 s18, 0x1f9000, s18
	s_add_u32 s14, s14, s18
	s_addc_u32 s15, s15, 0
	s_cmp_eq_u32 s0, 0x1080000
	s_cbranch_scc0 .Lscan_tile
	s_nop 11
	v_fmac_f32_e32 v234, v100, v162
	v_fmac_f32_e32 v235, v101, v163
	v_fmac_f32_e32 v236, v102, v164
	v_fmac_f32_e32 v237, v103, v165
	v_fmac_f32_e32 v238, v80, v166
	v_fmac_f32_e32 v239, v81, v167
	v_fmac_f32_e32 v240, v82, v192
	v_fmac_f32_e32 v241, v83, v193
	v_mul_f32_e32 v242, v234, v234
	v_mul_f32_e32 v243, v235, v235
	v_mul_f32_e32 v244, v236, v236
	v_mul_f32_e32 v245, v237, v237
	v_mul_f32_e32 v246, v238, v238
	v_mul_f32_e32 v247, v239, v239
	v_mul_f32_e32 v248, v240, v240
	v_mul_f32_e32 v249, v241, v241
	v_fmaak_f32 v242, v242, v184, 0xc0135761
	v_fmaak_f32 v243, v243, v184, 0xc0135761
	v_fmaak_f32 v244, v244, v184, 0xc0135761
	v_fmaak_f32 v245, v245, v184, 0xc0135761
	v_fmaak_f32 v246, v246, v184, 0xc0135761
	v_fmaak_f32 v247, v247, v184, 0xc0135761
	v_fmaak_f32 v248, v248, v184, 0xc0135761
	v_fmaak_f32 v249, v249, v184, 0xc0135761
	v_mul_f32_e32 v242, v234, v242
	v_mul_f32_e32 v243, v235, v243
	v_mul_f32_e32 v244, v236, v244
	v_mul_f32_e32 v245, v237, v245
	v_mul_f32_e32 v246, v238, v246
	v_mul_f32_e32 v247, v239, v247
	v_mul_f32_e32 v248, v240, v248
	v_mul_f32_e32 v249, v241, v249
	v_exp_f32_e32 v242, v242
	v_exp_f32_e32 v243, v243
	v_exp_f32_e32 v244, v244
	v_exp_f32_e32 v245, v245
	v_exp_f32_e32 v246, v246
	v_exp_f32_e32 v247, v247
	v_exp_f32_e32 v248, v248
	v_exp_f32_e32 v249, v249
	v_add_f32_e32 v242, 1.0, v242
	v_add_f32_e32 v243, 1.0, v243
	v_add_f32_e32 v244, 1.0, v244
	v_add_f32_e32 v245, 1.0, v245
	v_add_f32_e32 v246, 1.0, v246
	v_add_f32_e32 v247, 1.0, v247
	v_add_f32_e32 v248, 1.0, v248
	v_add_f32_e32 v249, 1.0, v249
	v_rcp_f32_e32 v242, v242
	v_rcp_f32_e32 v243, v243
	v_rcp_f32_e32 v244, v244
	v_rcp_f32_e32 v245, v245
	v_rcp_f32_e32 v246, v246
	v_rcp_f32_e32 v247, v247
	v_rcp_f32_e32 v248, v248
	v_rcp_f32_e32 v249, v249
	v_mul_f32_e32 v234, v234, v242
	v_mul_f32_e32 v235, v235, v243
	v_mul_f32_e32 v236, v236, v244
	v_mul_f32_e32 v237, v237, v245
	v_mul_f32_e32 v238, v238, v246
	v_mul_f32_e32 v239, v239, v247
	v_mul_f32_e32 v240, v240, v248
	v_mul_f32_e32 v241, v241, v249
	v_cvt_pk_bf16_f32 v242, v234, v235
	v_cvt_pk_bf16_f32 v243, v236, v237
	v_cvt_pk_bf16_f32 v244, v238, v239
	v_cvt_pk_bf16_f32 v245, v240, v241
	global_store_dwordx2 v253, v[242:243], s[14:15]
	global_store_dwordx2 v254, v[244:245], s[14:15]
	s_add_i32 s6, s6, s7
	s_add_i32 s10, s10, s11
	s_add_i32 s12, s12, s7
	s_cmpk_gt_i32 s6, 0x3ff
	s_cbranch_scc0 .LBB0_563
